# MLA with static priority for waves 4-7: second max chain interleaved with the PV MFMAs so waves 0-3 have almost no VALU behind their barrier
# speedup vs baseline: 1.0191x; 1.0032x over previous
; __device__ __forceinline__ void finishSM9(f32x16& p0, f32x16& p1, float alpha, float& l_reg, v8i32& p8) {
; #pragma unroll
;   for (int r = 0; r < 16; ++r) { p0[r] = __builtin_amdgcn_exp2f(p0[r]); p1[r] = __builtin_amdgcn_exp2f(p1[r]); }
;   float ps = 0;
; #pragma unroll
;   for (int r = 0; r < 16; ++r) ps += p0[r];
; #pragma unroll
;   for (int r = 0; r < 16; ++r) ps += p1[r];
;   { auto rr = __builtin_amdgcn_permlane32_swap(__float_as_uint(ps), __float_as_uint(ps), false, false);
;     ps = __uint_as_float(rr[0]) + __uint_as_float(rr[1]); }
;   l_reg = l_reg * alpha + ps;
; #pragma unroll
;   for (int g = 0; g < 4; ++g) {
;     int w = __builtin_amdgcn_cvt_pk_fp8_f32(p0[4 * g], p0[4 * g + 1], 0, false); p8[g] = __builtin_amdgcn_cvt_pk_fp8_f32(p0[4 * g + 2], p0[4 * g + 3], w, true);
;     int u = __builtin_amdgcn_cvt_pk_fp8_f32(p1[4 * g], p1[4 * g + 1], 0, false); p8[4 + g] = __builtin_amdgcn_cvt_pk_fp8_f32(p1[4 * g + 2], p1[4 * g + 3], u, true); }
; }
; __device__ __forceinline__ void pv8(f32x16* o, const char* Vt, const v8i32 p8, int r32, int hi) {
;   const int sw = (r32 >> 2) & 3, a0 = r32 * 64 + (((hi * 2) ^ sw) << 4), a1 = r32 * 64 + (((hi * 2 + 1) ^ sw) << 4);
; #pragma unroll
;   for (int d0 = 0; d0 < 4; ++d0) {
;     const v8i32 vf = cat8(*reinterpret_cast<const v4i32*>(Vt + d0 * 2048 + a0), *reinterpret_cast<const v4i32*>(Vt + d0 * 2048 + a1));
;     o[d0] = __builtin_amdgcn_mfma_scale_f32_32x32x64_f8f6f4(p8, vf, o[d0], 0, 0, 0, 127, 0, 127); }
; }
; __device__ __forceinline__ void qkt9(f32x16& p0, f32x16& p1, const char* Kn, const char* Kr, const v8i32* qf, const float init, int r32, int hi) {
; #pragma unroll
;   for (int r = 0; r < 16; ++r) { p0[r] = init; p1[r] = init; }
; #pragma unroll
;   for (int s = 0; s < 2; ++s) { const int c0 = s * 4 + hi * 2;
;     const v8i32 a0 = cat8(*reinterpret_cast<const v4i32*>(Kn + KN8SW(r32, c0)), *reinterpret_cast<const v4i32*>(Kn + KN8SW(r32, c0 + 1)));
;     const v8i32 a1 = cat8(*reinterpret_cast<const v4i32*>(Kn + 4096 + KN8SW(r32, c0)), *reinterpret_cast<const v4i32*>(Kn + 4096 + KN8SW(r32, c0 + 1)));
;     p0 = __builtin_amdgcn_mfma_scale_f32_32x32x64_f8f6f4(a0, qf[s], p0, 0, 0, 0, 127, 0, 124);
;     p1 = __builtin_amdgcn_mfma_scale_f32_32x32x64_f8f6f4(a1, qf[s], p1, 0, 0, 0, 127, 0, 124); }
;   { const int c0 = hi * 2;
.LBB0_1321:
	ds_read_b128 v[114:117], v215 offset:24576
	ds_read_b128 v[118:121], v216 offset:24576
	ds_read_b128 v[222:225], v215 offset:28672
	ds_read_b128 v[226:229], v216 offset:28672
	s_add_i32 m0, s98, 0xa800
	s_nop 0
	global_load_lds_dwordx4 v176, s[18:19]
	s_add_i32 m0, s98, 0xc800
	s_nop 0
	global_load_lds_dwordx4 v178, s[16:17]
	s_add_i32 m0, s98, 0xe800
	s_nop 0
	global_load_lds_dwordx4 v[180:181], off
	v_exp_f32_e32 v0, v82
	v_exp_f32_e32 v177, v83
	v_exp_f32_e32 v179, v84
	v_exp_f32_e32 v254, v85
	v_add_f32_e32 v219, v0, v177
	v_cvt_pk_fp8_f32 v246, v0, v177
	v_add_f32_e32 v219, v179, v219
	v_add_f32_e32 v219, v254, v219
	v_cvt_pk_fp8_f32 v246, v179, v254 op_sel:[0,0,1]
	s_waitcnt lgkmcnt(2)
	v_mfma_scale_f32_32x32x64_f8f6f4 v[114:129], v[114:121], v[146:153], v[230:245], v194, v193 op_sel_hi:[0,0,0]
	v_exp_f32_e32 v0, v86
	v_exp_f32_e32 v177, v87
	v_exp_f32_e32 v179, v88
	v_exp_f32_e32 v254, v89
	v_add_f32_e32 v219, v0, v219
	v_add_f32_e32 v219, v177, v219
	v_cvt_pk_fp8_f32 v247, v0, v177
	v_add_f32_e32 v219, v179, v219
	v_add_f32_e32 v219, v254, v219
	v_cvt_pk_fp8_f32 v247, v179, v254 op_sel:[0,0,1]
	ds_read_b128 v[82:85], v213 offset:24576
	ds_read_b128 v[86:89], v214 offset:24576
	s_waitcnt lgkmcnt(2)
	v_mfma_scale_f32_32x32x64_f8f6f4 v[98:113], v[222:229], v[146:153], v[230:245], v194, v193 op_sel_hi:[0,0,0]
	ds_read_b128 v[222:225], v213 offset:28672
	ds_read_b128 v[226:229], v214 offset:28672
	v_exp_f32_e32 v0, v90
	v_exp_f32_e32 v177, v91
	v_exp_f32_e32 v179, v92
	v_exp_f32_e32 v254, v93
	v_add_f32_e32 v219, v0, v219
	v_add_f32_e32 v219, v177, v219
	v_cvt_pk_fp8_f32 v248, v0, v177
	v_add_f32_e32 v219, v179, v219
	v_add_f32_e32 v219, v254, v219
	v_cvt_pk_fp8_f32 v248, v179, v254 op_sel:[0,0,1]
	v_exp_f32_e32 v0, v94
	v_exp_f32_e32 v177, v95
	v_exp_f32_e32 v179, v96
	v_exp_f32_e32 v254, v97
	v_add_f32_e32 v219, v0, v219
	v_add_f32_e32 v219, v177, v219
	v_cvt_pk_fp8_f32 v249, v0, v177
	v_add_f32_e32 v219, v179, v219
	v_add_f32_e32 v219, v254, v219
	v_cvt_pk_fp8_f32 v249, v179, v254 op_sel:[0,0,1]
	ds_read_b128 v[90:93], v185 offset:36864
	ds_read_b128 v[94:97], v186 offset:36864
	s_waitcnt lgkmcnt(4)
	v_mfma_scale_f32_32x32x64_f8f6f4 v[114:129], v[82:89], v[138:145], v[114:129], v194, v193 op_sel_hi:[0,0,0]
	v_exp_f32_e32 v0, v66
	v_exp_f32_e32 v177, v67
	v_exp_f32_e32 v179, v68
	v_exp_f32_e32 v254, v69
	v_add_f32_e32 v219, v0, v219
	v_add_f32_e32 v219, v177, v219
	v_cvt_pk_fp8_f32 v250, v0, v177
	v_add_f32_e32 v219, v179, v219
	v_add_f32_e32 v219, v254, v219
	v_cvt_pk_fp8_f32 v250, v179, v254 op_sel:[0,0,1]
	s_waitcnt lgkmcnt(2)
	v_mfma_scale_f32_32x32x64_f8f6f4 v[98:113], v[222:229], v[138:145], v[98:113], v194, v193 op_sel_hi:[0,0,0]
	ds_read_b128 v[222:225], v185 offset:38912
	ds_read_b128 v[226:229], v186 offset:38912
	v_exp_f32_e32 v0, v70
	v_exp_f32_e32 v177, v71
	v_exp_f32_e32 v179, v72
	v_exp_f32_e32 v254, v73
	v_add_f32_e32 v219, v0, v219
	v_add_f32_e32 v219, v177, v219
	v_cvt_pk_fp8_f32 v251, v0, v177
	v_add_f32_e32 v219, v179, v219
	v_add_f32_e32 v219, v254, v219
	v_cvt_pk_fp8_f32 v251, v179, v254 op_sel:[0,0,1]
	v_exp_f32_e32 v0, v74
	v_exp_f32_e32 v177, v75
	v_exp_f32_e32 v179, v76
	v_exp_f32_e32 v254, v77
	v_add_f32_e32 v219, v0, v219
	v_add_f32_e32 v219, v177, v219
	v_cvt_pk_fp8_f32 v252, v0, v177
	v_add_f32_e32 v219, v179, v219
	v_add_f32_e32 v219, v254, v219
	v_cvt_pk_fp8_f32 v252, v179, v254 op_sel:[0,0,1]
	s_waitcnt lgkmcnt(2)
	v_mfma_scale_f32_32x32x64_f8f6f4 v[114:129], v[90:97], v[130:137], v[114:129], v194, v193 op_sel_hi:[0,0,0]
	v_exp_f32_e32 v0, v78
	v_exp_f32_e32 v177, v79
	v_exp_f32_e32 v179, v80
	v_exp_f32_e32 v254, v81
	v_add_f32_e32 v219, v0, v219
	v_add_f32_e32 v219, v177, v219
	v_cvt_pk_fp8_f32 v253, v0, v177
	v_add_f32_e32 v219, v179, v219
	v_add_f32_e32 v219, v254, v219
	v_cvt_pk_fp8_f32 v253, v179, v254 op_sel:[0,0,1]
	ds_read_b128 v[90:93], v185 offset:0
	ds_read_b128 v[94:97], v186 offset:0
	ds_read_b128 v[82:85], v185 offset:2048
	ds_read_b128 v[86:89], v186 offset:2048
	ds_read_b128 v[74:77], v185 offset:4096
	ds_read_b128 v[78:81], v186 offset:4096
	ds_read_b128 v[66:69], v185 offset:6144
	ds_read_b128 v[70:73], v186 offset:6144
	s_waitcnt lgkmcnt(8)
	v_mfma_scale_f32_32x32x64_f8f6f4 v[98:113], v[222:229], v[130:137], v[98:113], v194, v193 op_sel_hi:[0,0,0]
	v_mov_b32_e32 v0, v219
	s_nop 1
	v_permlane32_swap_b32_e32 v219, v0
	v_add_f32_e32 v219, v219, v0
	v_fma_f32 v209, v209, v218, v219
	v_add_u32_e32 v176, 0x2000, v176
	v_add_u32_e32 v178, 0x20000, v178
	s_mov_b64 s[20:21], 0x1000
	v_lshl_add_u64 v[180:181], v[180:181], 0, s[20:21]
	v_max_f32_e32 v177, v114, v115
	v_max3_f32 v177, v177, v116, v117
	v_max3_f32 v177, v177, v118, v119
	v_max3_f32 v177, v177, v120, v121
	v_max3_f32 v177, v177, v122, v123
	v_max3_f32 v177, v177, v124, v125
	v_max3_f32 v177, v177, v126, v127
	v_max3_f32 v177, v177, v128, v129
	s_waitcnt lgkmcnt(6)
	v_mfma_scale_f32_32x32x64_f8f6f4 v[50:65], v[246:253], v[90:97], v[50:65], v194, v194 op_sel_hi:[0,0,0]
	v_max_f32_e32 v0, v98, v99
	v_max3_f32 v0, v0, v100, v101
	v_max3_f32 v0, v0, v102, v103
	s_waitcnt lgkmcnt(4)
	v_mfma_scale_f32_32x32x64_f8f6f4 v[34:49], v[246:253], v[82:89], v[34:49], v194, v194 op_sel_hi:[0,0,0]
	v_max3_f32 v0, v0, v104, v105
	v_max3_f32 v0, v0, v106, v107
	v_max3_f32 v0, v0, v108, v109
	s_waitcnt lgkmcnt(2)
	v_mfma_scale_f32_32x32x64_f8f6f4 v[18:33], v[246:253], v[74:81], v[18:33], v194, v194 op_sel_hi:[0,0,0]
	v_max3_f32 v0, v0, v110, v111
	v_max3_f32 v0, v0, v112, v113
	v_max_f32_e32 v177, v177, v0
	v_mov_b32_e32 v0, v177
	v_mov_b32_e32 v221, 1.0
	s_waitcnt lgkmcnt(0)
	v_mfma_scale_f32_32x32x64_f8f6f4 v[2:17], v[246:253], v[66:73], v[2:17], v194, v194 op_sel_hi:[0,0,0]
	s_waitcnt vmcnt(0)
	s_waitcnt lgkmcnt(0)
	s_barrier
	v_permlane32_swap_b32_e32 v177, v0
	v_max_f32_e32 v177, v177, v0
	v_cmp_ge_f32_e32 vcc, s90, v177
	s_cmp_eq_u64 vcc, exec
	s_cbranch_scc0 .Lmla_h0_newmax
; __device__ __forceinline__ void finishSM9(f32x16& p0, f32x16& p1, float alpha, float& l_reg, v8i32& p8) {
; #pragma unroll
;   for (int r = 0; r < 16; ++r) { p0[r] = __builtin_amdgcn_exp2f(p0[r]); p1[r] = __builtin_amdgcn_exp2f(p1[r]); }
;   float ps = 0;
; #pragma unroll
;   for (int r = 0; r < 16; ++r) ps += p0[r];
; #pragma unroll
;   for (int r = 0; r < 16; ++r) ps += p1[r];
;   { auto rr = __builtin_amdgcn_permlane32_swap(__float_as_uint(ps), __float_as_uint(ps), false, false);
;     ps = __uint_as_float(rr[0]) + __uint_as_float(rr[1]); }
;   l_reg = l_reg * alpha + ps;
; #pragma unroll
;   for (int g = 0; g < 4; ++g) {
;     int w = __builtin_amdgcn_cvt_pk_fp8_f32(p0[4 * g], p0[4 * g + 1], 0, false); p8[g] = __builtin_amdgcn_cvt_pk_fp8_f32(p0[4 * g + 2], p0[4 * g + 3], w, true);
;     int u = __builtin_amdgcn_cvt_pk_fp8_f32(p1[4 * g], p1[4 * g + 1], 0, false); p8[4 + g] = __builtin_amdgcn_cvt_pk_fp8_f32(p1[4 * g + 2], p1[4 * g + 3], u, true); }
; }
; __device__ __forceinline__ void pv8(f32x16* o, const char* Vt, const v8i32 p8, int r32, int hi) {
;   const int sw = (r32 >> 2) & 3, a0 = r32 * 64 + (((hi * 2) ^ sw) << 4), a1 = r32 * 64 + (((hi * 2 + 1) ^ sw) << 4);
; #pragma unroll
;   for (int d0 = 0; d0 < 4; ++d0) {
;     const v8i32 vf = cat8(*reinterpret_cast<const v4i32*>(Vt + d0 * 2048 + a0), *reinterpret_cast<const v4i32*>(Vt + d0 * 2048 + a1));
;     o[d0] = __builtin_amdgcn_mfma_scale_f32_32x32x64_f8f6f4(p8, vf, o[d0], 0, 0, 0, 127, 0, 127); }
; }
; __device__ __forceinline__ void qkt9(f32x16& p0, f32x16& p1, const char* Kn, const char* Kr, const v8i32* qf, const float init, int r32, int hi) {
; #pragma unroll
;   for (int r = 0; r < 16; ++r) { p0[r] = init; p1[r] = init; }
; #pragma unroll
;   for (int s = 0; s < 2; ++s) { const int c0 = s * 4 + hi * 2;
;     const v8i32 a0 = cat8(*reinterpret_cast<const v4i32*>(Kn + KN8SW(r32, c0)), *reinterpret_cast<const v4i32*>(Kn + KN8SW(r32, c0 + 1)));
;     const v8i32 a1 = cat8(*reinterpret_cast<const v4i32*>(Kn + 4096 + KN8SW(r32, c0)), *reinterpret_cast<const v4i32*>(Kn + 4096 + KN8SW(r32, c0 + 1)));
;     p0 = __builtin_amdgcn_mfma_scale_f32_32x32x64_f8f6f4(a0, qf[s], p0, 0, 0, 0, 127, 0, 124);
;     p1 = __builtin_amdgcn_mfma_scale_f32_32x32x64_f8f6f4(a1, qf[s], p1, 0, 0, 0, 127, 0, 124); }
;   { const int c0 = hi * 2;
.Lmla_h0_cont:
	ds_read_b128 v[82:85], v215 offset:51200
	ds_read_b128 v[86:89], v216 offset:51200
	ds_read_b128 v[222:225], v215 offset:55296
	ds_read_b128 v[226:229], v216 offset:55296
	s_add_i32 m0, s98, 0x0
	s_nop 0
	global_load_lds_dwordx4 v176, s[18:19]
	s_add_i32 m0, s98, 0x4000
	s_nop 0
	global_load_lds_dwordx4 v178, s[16:17]
	s_add_i32 m0, s98, 0x8000
	s_nop 0
	global_load_lds_dwordx4 v[180:181], off
	v_exp_f32_e32 v0, v114
	v_exp_f32_e32 v177, v115
	v_exp_f32_e32 v179, v116
	v_exp_f32_e32 v254, v117
	v_add_f32_e32 v219, v0, v177
	v_cvt_pk_fp8_f32 v246, v0, v177
	v_add_f32_e32 v219, v179, v219
	v_add_f32_e32 v219, v254, v219
	v_cvt_pk_fp8_f32 v246, v179, v254 op_sel:[0,0,1]
	s_waitcnt lgkmcnt(2)
	v_mfma_scale_f32_32x32x64_f8f6f4 v[82:97], v[82:89], v[146:153], v[230:245], v194, v193 op_sel_hi:[0,0,0]
	v_exp_f32_e32 v0, v118
	v_exp_f32_e32 v177, v119
	v_exp_f32_e32 v179, v120
	v_exp_f32_e32 v254, v121
	v_add_f32_e32 v219, v0, v219
	v_add_f32_e32 v219, v177, v219
	v_cvt_pk_fp8_f32 v247, v0, v177
	v_add_f32_e32 v219, v179, v219
	v_add_f32_e32 v219, v254, v219
	v_cvt_pk_fp8_f32 v247, v179, v254 op_sel:[0,0,1]
	ds_read_b128 v[114:117], v213 offset:51200
	ds_read_b128 v[118:121], v214 offset:51200
	s_waitcnt lgkmcnt(2)
	v_mfma_scale_f32_32x32x64_f8f6f4 v[66:81], v[222:229], v[146:153], v[230:245], v194, v193 op_sel_hi:[0,0,0]
	ds_read_b128 v[222:225], v213 offset:55296
	ds_read_b128 v[226:229], v214 offset:55296
	v_exp_f32_e32 v0, v122
	v_exp_f32_e32 v177, v123
	v_exp_f32_e32 v179, v124
	v_exp_f32_e32 v254, v125
	v_add_f32_e32 v219, v0, v219
	v_add_f32_e32 v219, v177, v219
	v_cvt_pk_fp8_f32 v248, v0, v177
	v_add_f32_e32 v219, v179, v219
	v_add_f32_e32 v219, v254, v219
	v_cvt_pk_fp8_f32 v248, v179, v254 op_sel:[0,0,1]
	v_exp_f32_e32 v0, v126
	v_exp_f32_e32 v177, v127
	v_exp_f32_e32 v179, v128
	v_exp_f32_e32 v254, v129
	v_add_f32_e32 v219, v0, v219
	v_add_f32_e32 v219, v177, v219
	v_cvt_pk_fp8_f32 v249, v0, v177
	v_add_f32_e32 v219, v179, v219
	v_add_f32_e32 v219, v254, v219
	v_cvt_pk_fp8_f32 v249, v179, v254 op_sel:[0,0,1]
	ds_read_b128 v[122:125], v185 offset:59392
	ds_read_b128 v[126:129], v186 offset:59392
	s_waitcnt lgkmcnt(4)
	v_mfma_scale_f32_32x32x64_f8f6f4 v[82:97], v[114:121], v[138:145], v[82:97], v194, v193 op_sel_hi:[0,0,0]
	v_exp_f32_e32 v0, v98
	v_exp_f32_e32 v177, v99
	v_exp_f32_e32 v179, v100
	v_exp_f32_e32 v254, v101
	v_add_f32_e32 v219, v0, v219
	v_add_f32_e32 v219, v177, v219
	v_cvt_pk_fp8_f32 v250, v0, v177
	v_add_f32_e32 v219, v179, v219
	v_add_f32_e32 v219, v254, v219
	v_cvt_pk_fp8_f32 v250, v179, v254 op_sel:[0,0,1]
	s_waitcnt lgkmcnt(2)
	v_mfma_scale_f32_32x32x64_f8f6f4 v[66:81], v[222:229], v[138:145], v[66:81], v194, v193 op_sel_hi:[0,0,0]
	ds_read_b128 v[222:225], v185 offset:61440
	ds_read_b128 v[226:229], v186 offset:61440
	v_exp_f32_e32 v0, v102
	v_exp_f32_e32 v177, v103
	v_exp_f32_e32 v179, v104
	v_exp_f32_e32 v254, v105
	v_add_f32_e32 v219, v0, v219
	v_add_f32_e32 v219, v177, v219
	v_cvt_pk_fp8_f32 v251, v0, v177
	v_add_f32_e32 v219, v179, v219
	v_add_f32_e32 v219, v254, v219
	v_cvt_pk_fp8_f32 v251, v179, v254 op_sel:[0,0,1]
	v_exp_f32_e32 v0, v106
	v_exp_f32_e32 v177, v107
	v_exp_f32_e32 v179, v108
	v_exp_f32_e32 v254, v109
	v_add_f32_e32 v219, v0, v219
	v_add_f32_e32 v219, v177, v219
	v_cvt_pk_fp8_f32 v252, v0, v177
	v_add_f32_e32 v219, v179, v219
	v_add_f32_e32 v219, v254, v219
	v_cvt_pk_fp8_f32 v252, v179, v254 op_sel:[0,0,1]
	s_waitcnt lgkmcnt(2)
	v_mfma_scale_f32_32x32x64_f8f6f4 v[82:97], v[122:129], v[130:137], v[82:97], v194, v193 op_sel_hi:[0,0,0]
	v_exp_f32_e32 v0, v110
	v_exp_f32_e32 v177, v111
	v_exp_f32_e32 v179, v112
	v_exp_f32_e32 v254, v113
	v_add_f32_e32 v219, v0, v219
	v_add_f32_e32 v219, v177, v219
	v_cvt_pk_fp8_f32 v253, v0, v177
	v_add_f32_e32 v219, v179, v219
	v_add_f32_e32 v219, v254, v219
	v_cvt_pk_fp8_f32 v253, v179, v254 op_sel:[0,0,1]
	ds_read_b128 v[122:125], v185 offset:8192
	ds_read_b128 v[126:129], v186 offset:8192
	ds_read_b128 v[114:117], v185 offset:10240
	ds_read_b128 v[118:121], v186 offset:10240
	ds_read_b128 v[106:109], v185 offset:12288
	ds_read_b128 v[110:113], v186 offset:12288
	ds_read_b128 v[98:101], v185 offset:14336
	ds_read_b128 v[102:105], v186 offset:14336
	s_waitcnt lgkmcnt(8)
	v_mfma_scale_f32_32x32x64_f8f6f4 v[66:81], v[222:229], v[130:137], v[66:81], v194, v193 op_sel_hi:[0,0,0]
	v_mov_b32_e32 v0, v219
	s_nop 1
	v_permlane32_swap_b32_e32 v219, v0
	v_add_f32_e32 v219, v219, v0
	v_fma_f32 v209, v209, v221, v219
	v_add_u32_e32 v176, 0x2000, v176
	v_add_u32_e32 v178, 0x20000, v178
	s_mov_b64 s[20:21], 0x1000
	v_lshl_add_u64 v[180:181], v[180:181], 0, s[20:21]
	v_max_f32_e32 v177, v82, v83
	v_max3_f32 v177, v177, v84, v85
	v_max3_f32 v177, v177, v86, v87
	v_max3_f32 v177, v177, v88, v89
	v_max3_f32 v177, v177, v90, v91
	v_max3_f32 v177, v177, v92, v93
	v_max3_f32 v177, v177, v94, v95
	v_max3_f32 v177, v177, v96, v97
	s_waitcnt lgkmcnt(6)
	v_mfma_scale_f32_32x32x64_f8f6f4 v[50:65], v[246:253], v[122:129], v[50:65], v194, v194 op_sel_hi:[0,0,0]
	v_max_f32_e32 v0, v66, v67
	v_max3_f32 v0, v0, v68, v69
	v_max3_f32 v0, v0, v70, v71
	s_waitcnt lgkmcnt(4)
	v_mfma_scale_f32_32x32x64_f8f6f4 v[34:49], v[246:253], v[114:121], v[34:49], v194, v194 op_sel_hi:[0,0,0]
	v_max3_f32 v0, v0, v72, v73
	v_max3_f32 v0, v0, v74, v75
	v_max3_f32 v0, v0, v76, v77
	s_waitcnt lgkmcnt(2)
	v_mfma_scale_f32_32x32x64_f8f6f4 v[18:33], v[246:253], v[106:113], v[18:33], v194, v194 op_sel_hi:[0,0,0]
	v_max3_f32 v0, v0, v78, v79
	v_max3_f32 v0, v0, v80, v81
	v_max_f32_e32 v177, v177, v0
	v_mov_b32_e32 v0, v177
	v_mov_b32_e32 v218, 1.0
	s_waitcnt lgkmcnt(0)
	v_mfma_scale_f32_32x32x64_f8f6f4 v[2:17], v[246:253], v[98:105], v[2:17], v194, v194 op_sel_hi:[0,0,0]
	s_waitcnt vmcnt(0)
	s_waitcnt lgkmcnt(0)
	s_barrier
	v_permlane32_swap_b32_e32 v177, v0
	v_max_f32_e32 v177, v177, v0
	v_cmp_ge_f32_e32 vcc, s90, v177
	s_cmp_eq_u64 vcc, exec
	s_cbranch_scc0 .Lmla_h1_newmax
; __device__ __forceinline__ void finishSM9(f32x16& p0, f32x16& p1, float alpha, float& l_reg, v8i32& p8) {
; #pragma unroll
;   for (int r = 0; r < 16; ++r) { p0[r] = __builtin_amdgcn_exp2f(p0[r]); p1[r] = __builtin_amdgcn_exp2f(p1[r]); }
;   float ps = 0;
; #pragma unroll
;   for (int r = 0; r < 16; ++r) ps += p0[r];
; #pragma unroll
;   for (int r = 0; r < 16; ++r) ps += p1[r];
;   { auto rr = __builtin_amdgcn_permlane32_swap(__float_as_uint(ps), __float_as_uint(ps), false, false);
;     ps = __uint_as_float(rr[0]) + __uint_as_float(rr[1]); }
;   l_reg = l_reg * alpha + ps;
; #pragma unroll
;   for (int g = 0; g < 4; ++g) {
;     int w = __builtin_amdgcn_cvt_pk_fp8_f32(p0[4 * g], p0[4 * g + 1], 0, false); p8[g] = __builtin_amdgcn_cvt_pk_fp8_f32(p0[4 * g + 2], p0[4 * g + 3], w, true);
;     int u = __builtin_amdgcn_cvt_pk_fp8_f32(p1[4 * g], p1[4 * g + 1], 0, false); p8[4 + g] = __builtin_amdgcn_cvt_pk_fp8_f32(p1[4 * g + 2], p1[4 * g + 3], u, true); }
; }
; __device__ __forceinline__ void pv8(f32x16* o, const char* Vt, const v8i32 p8, int r32, int hi) {
;   const int sw = (r32 >> 2) & 3, a0 = r32 * 64 + (((hi * 2) ^ sw) << 4), a1 = r32 * 64 + (((hi * 2 + 1) ^ sw) << 4);
; #pragma unroll
;   for (int d0 = 0; d0 < 4; ++d0) {
;     const v8i32 vf = cat8(*reinterpret_cast<const v4i32*>(Vt + d0 * 2048 + a0), *reinterpret_cast<const v4i32*>(Vt + d0 * 2048 + a1));
;     o[d0] = __builtin_amdgcn_mfma_scale_f32_32x32x64_f8f6f4(p8, vf, o[d0], 0, 0, 0, 127, 0, 127); }
; }
; __device__ __forceinline__ void qkt9(f32x16& p0, f32x16& p1, const char* Kn, const char* Kr, const v8i32* qf, const float init, int r32, int hi) {
; #pragma unroll
;   for (int r = 0; r < 16; ++r) { p0[r] = init; p1[r] = init; }
; #pragma unroll
;   for (int s = 0; s < 2; ++s) { const int c0 = s * 4 + hi * 2;
;     const v8i32 a0 = cat8(*reinterpret_cast<const v4i32*>(Kn + KN8SW(r32, c0)), *reinterpret_cast<const v4i32*>(Kn + KN8SW(r32, c0 + 1)));
;     const v8i32 a1 = cat8(*reinterpret_cast<const v4i32*>(Kn + 4096 + KN8SW(r32, c0)), *reinterpret_cast<const v4i32*>(Kn + 4096 + KN8SW(r32, c0 + 1)));
;     p0 = __builtin_amdgcn_mfma_scale_f32_32x32x64_f8f6f4(a0, qf[s], p0, 0, 0, 0, 127, 0, 124);
;     p1 = __builtin_amdgcn_mfma_scale_f32_32x32x64_f8f6f4(a1, qf[s], p1, 0, 0, 0, 127, 0, 124); }
;   { const int c0 = hi * 2;
.Lmla_h1_cont:
	ds_read_b128 v[114:117], v215 offset:16384
	ds_read_b128 v[118:121], v216 offset:16384
	ds_read_b128 v[222:225], v215 offset:20480
	ds_read_b128 v[226:229], v216 offset:20480
	s_add_i32 m0, s98, 0x2000
	s_nop 0
	global_load_lds_dwordx4 v176, s[18:19]
	s_add_i32 m0, s98, 0x6000
	s_nop 0
	global_load_lds_dwordx4 v178, s[16:17]
	s_add_i32 m0, s98, 0x9000
	s_nop 0
	global_load_lds_dwordx4 v[180:181], off
	v_exp_f32_e32 v0, v82
	v_exp_f32_e32 v177, v83
	v_exp_f32_e32 v179, v84
	v_exp_f32_e32 v254, v85
	v_add_f32_e32 v219, v0, v177
	v_cvt_pk_fp8_f32 v246, v0, v177
	v_add_f32_e32 v219, v179, v219
	v_add_f32_e32 v219, v254, v219
	v_cvt_pk_fp8_f32 v246, v179, v254 op_sel:[0,0,1]
	s_waitcnt lgkmcnt(2)
	v_mfma_scale_f32_32x32x64_f8f6f4 v[114:129], v[114:121], v[146:153], v[230:245], v194, v193 op_sel_hi:[0,0,0]
	v_exp_f32_e32 v0, v86
	v_exp_f32_e32 v177, v87
	v_exp_f32_e32 v179, v88
	v_exp_f32_e32 v254, v89
	v_add_f32_e32 v219, v0, v219
	v_add_f32_e32 v219, v177, v219
	v_cvt_pk_fp8_f32 v247, v0, v177
	v_add_f32_e32 v219, v179, v219
	v_add_f32_e32 v219, v254, v219
	v_cvt_pk_fp8_f32 v247, v179, v254 op_sel:[0,0,1]
	ds_read_b128 v[82:85], v213 offset:16384
	ds_read_b128 v[86:89], v214 offset:16384
	s_waitcnt lgkmcnt(2)
	v_mfma_scale_f32_32x32x64_f8f6f4 v[98:113], v[222:229], v[146:153], v[230:245], v194, v193 op_sel_hi:[0,0,0]
	ds_read_b128 v[222:225], v213 offset:20480
	ds_read_b128 v[226:229], v214 offset:20480
	v_exp_f32_e32 v0, v90
	v_exp_f32_e32 v177, v91
	v_exp_f32_e32 v179, v92
	v_exp_f32_e32 v254, v93
	v_add_f32_e32 v219, v0, v219
	v_add_f32_e32 v219, v177, v219
	v_cvt_pk_fp8_f32 v248, v0, v177
	v_add_f32_e32 v219, v179, v219
	v_add_f32_e32 v219, v254, v219
	v_cvt_pk_fp8_f32 v248, v179, v254 op_sel:[0,0,1]
	v_exp_f32_e32 v0, v94
	v_exp_f32_e32 v177, v95
	v_exp_f32_e32 v179, v96
	v_exp_f32_e32 v254, v97
	v_add_f32_e32 v219, v0, v219
	v_add_f32_e32 v219, v177, v219
	v_cvt_pk_fp8_f32 v249, v0, v177
	v_add_f32_e32 v219, v179, v219
	v_add_f32_e32 v219, v254, v219
	v_cvt_pk_fp8_f32 v249, v179, v254 op_sel:[0,0,1]
	ds_read_b128 v[90:93], v185 offset:32768
	ds_read_b128 v[94:97], v186 offset:32768
	s_waitcnt lgkmcnt(4)
	v_mfma_scale_f32_32x32x64_f8f6f4 v[114:129], v[82:89], v[138:145], v[114:129], v194, v193 op_sel_hi:[0,0,0]
	v_exp_f32_e32 v0, v66
	v_exp_f32_e32 v177, v67
	v_exp_f32_e32 v179, v68
	v_exp_f32_e32 v254, v69
	v_add_f32_e32 v219, v0, v219
	v_add_f32_e32 v219, v177, v219
	v_cvt_pk_fp8_f32 v250, v0, v177
	v_add_f32_e32 v219, v179, v219
	v_add_f32_e32 v219, v254, v219
	v_cvt_pk_fp8_f32 v250, v179, v254 op_sel:[0,0,1]
	s_waitcnt lgkmcnt(2)
	v_mfma_scale_f32_32x32x64_f8f6f4 v[98:113], v[222:229], v[138:145], v[98:113], v194, v193 op_sel_hi:[0,0,0]
	ds_read_b128 v[222:225], v185 offset:34816
	ds_read_b128 v[226:229], v186 offset:34816
	v_exp_f32_e32 v0, v70
	v_exp_f32_e32 v177, v71
	v_exp_f32_e32 v179, v72
	v_exp_f32_e32 v254, v73
	v_add_f32_e32 v219, v0, v219
	v_add_f32_e32 v219, v177, v219
	v_cvt_pk_fp8_f32 v251, v0, v177
	v_add_f32_e32 v219, v179, v219
	v_add_f32_e32 v219, v254, v219
	v_cvt_pk_fp8_f32 v251, v179, v254 op_sel:[0,0,1]
	v_exp_f32_e32 v0, v74
	v_exp_f32_e32 v177, v75
	v_exp_f32_e32 v179, v76
	v_exp_f32_e32 v254, v77
	v_add_f32_e32 v219, v0, v219
	v_add_f32_e32 v219, v177, v219
	v_cvt_pk_fp8_f32 v252, v0, v177
	v_add_f32_e32 v219, v179, v219
	v_add_f32_e32 v219, v254, v219
	v_cvt_pk_fp8_f32 v252, v179, v254 op_sel:[0,0,1]
	s_waitcnt lgkmcnt(2)
	v_mfma_scale_f32_32x32x64_f8f6f4 v[114:129], v[90:97], v[130:137], v[114:129], v194, v193 op_sel_hi:[0,0,0]
	v_exp_f32_e32 v0, v78
	v_exp_f32_e32 v177, v79
	v_exp_f32_e32 v179, v80
	v_exp_f32_e32 v254, v81
	v_add_f32_e32 v219, v0, v219
	v_add_f32_e32 v219, v177, v219
	v_cvt_pk_fp8_f32 v253, v0, v177
	v_add_f32_e32 v219, v179, v219
	v_add_f32_e32 v219, v254, v219
	v_cvt_pk_fp8_f32 v253, v179, v254 op_sel:[0,0,1]
	ds_read_b128 v[90:93], v185 offset:43008
	ds_read_b128 v[94:97], v186 offset:43008
	ds_read_b128 v[82:85], v185 offset:45056
	ds_read_b128 v[86:89], v186 offset:45056
	ds_read_b128 v[74:77], v185 offset:47104
	ds_read_b128 v[78:81], v186 offset:47104
	ds_read_b128 v[66:69], v185 offset:49152
	ds_read_b128 v[70:73], v186 offset:49152
	s_waitcnt lgkmcnt(8)
	v_mfma_scale_f32_32x32x64_f8f6f4 v[98:113], v[222:229], v[130:137], v[98:113], v194, v193 op_sel_hi:[0,0,0]
	v_mov_b32_e32 v0, v219
	s_nop 1
	v_permlane32_swap_b32_e32 v219, v0
	v_add_f32_e32 v219, v219, v0
	v_fma_f32 v209, v209, v218, v219
	v_add_u32_e32 v176, 0x2000, v176
	v_add_u32_e32 v178, 0x20000, v178
	s_mov_b64 s[20:21], 0x1000
	v_lshl_add_u64 v[180:181], v[180:181], 0, s[20:21]
	v_max_f32_e32 v177, v114, v115
	v_max3_f32 v177, v177, v116, v117
	v_max3_f32 v177, v177, v118, v119
	v_max3_f32 v177, v177, v120, v121
	v_max3_f32 v177, v177, v122, v123
	v_max3_f32 v177, v177, v124, v125
	v_max3_f32 v177, v177, v126, v127
	v_max3_f32 v177, v177, v128, v129
	s_waitcnt lgkmcnt(6)
	v_mfma_scale_f32_32x32x64_f8f6f4 v[50:65], v[246:253], v[90:97], v[50:65], v194, v194 op_sel_hi:[0,0,0]
	v_max_f32_e32 v0, v98, v99
	v_max3_f32 v0, v0, v100, v101
	v_max3_f32 v0, v0, v102, v103
	s_waitcnt lgkmcnt(4)
	v_mfma_scale_f32_32x32x64_f8f6f4 v[34:49], v[246:253], v[82:89], v[34:49], v194, v194 op_sel_hi:[0,0,0]
	v_max3_f32 v0, v0, v104, v105
	v_max3_f32 v0, v0, v106, v107
	v_max3_f32 v0, v0, v108, v109
	s_waitcnt lgkmcnt(2)
	v_mfma_scale_f32_32x32x64_f8f6f4 v[18:33], v[246:253], v[74:81], v[18:33], v194, v194 op_sel_hi:[0,0,0]
	v_max3_f32 v0, v0, v110, v111
	v_max3_f32 v0, v0, v112, v113
	v_max_f32_e32 v177, v177, v0
	v_mov_b32_e32 v0, v177
	v_mov_b32_e32 v221, 1.0
	s_waitcnt lgkmcnt(0)
	v_mfma_scale_f32_32x32x64_f8f6f4 v[2:17], v[246:253], v[66:73], v[2:17], v194, v194 op_sel_hi:[0,0,0]
	s_waitcnt vmcnt(0)
	s_waitcnt lgkmcnt(0)
	s_barrier
	v_permlane32_swap_b32_e32 v177, v0
	v_max_f32_e32 v177, v177, v0
	v_cmp_ge_f32_e32 vcc, s90, v177
	s_cmp_eq_u64 vcc, exec
	s_cbranch_scc0 .Lmla_h2_newmax
; __device__ __forceinline__ void finishSM9(f32x16& p0, f32x16& p1, float alpha, float& l_reg, v8i32& p8) {
; #pragma unroll
;   for (int r = 0; r < 16; ++r) { p0[r] = __builtin_amdgcn_exp2f(p0[r]); p1[r] = __builtin_amdgcn_exp2f(p1[r]); }
;   float ps = 0;
; #pragma unroll
;   for (int r = 0; r < 16; ++r) ps += p0[r];
; #pragma unroll
;   for (int r = 0; r < 16; ++r) ps += p1[r];
;   { auto rr = __builtin_amdgcn_permlane32_swap(__float_as_uint(ps), __float_as_uint(ps), false, false);
;     ps = __uint_as_float(rr[0]) + __uint_as_float(rr[1]); }
;   l_reg = l_reg * alpha + ps;
; #pragma unroll
;   for (int g = 0; g < 4; ++g) {
;     int w = __builtin_amdgcn_cvt_pk_fp8_f32(p0[4 * g], p0[4 * g + 1], 0, false); p8[g] = __builtin_amdgcn_cvt_pk_fp8_f32(p0[4 * g + 2], p0[4 * g + 3], w, true);
;     int u = __builtin_amdgcn_cvt_pk_fp8_f32(p1[4 * g], p1[4 * g + 1], 0, false); p8[4 + g] = __builtin_amdgcn_cvt_pk_fp8_f32(p1[4 * g + 2], p1[4 * g + 3], u, true); }
; }
; __device__ __forceinline__ void pv8(f32x16* o, const char* Vt, const v8i32 p8, int r32, int hi) {
;   const int sw = (r32 >> 2) & 3, a0 = r32 * 64 + (((hi * 2) ^ sw) << 4), a1 = r32 * 64 + (((hi * 2 + 1) ^ sw) << 4);
; #pragma unroll
;   for (int d0 = 0; d0 < 4; ++d0) {
;     const v8i32 vf = cat8(*reinterpret_cast<const v4i32*>(Vt + d0 * 2048 + a0), *reinterpret_cast<const v4i32*>(Vt + d0 * 2048 + a1));
;     o[d0] = __builtin_amdgcn_mfma_scale_f32_32x32x64_f8f6f4(p8, vf, o[d0], 0, 0, 0, 127, 0, 127); }
; }
; __device__ __forceinline__ void qkt9(f32x16& p0, f32x16& p1, const char* Kn, const char* Kr, const v8i32* qf, const float init, int r32, int hi) {
; #pragma unroll
;   for (int r = 0; r < 16; ++r) { p0[r] = init; p1[r] = init; }
; #pragma unroll
;   for (int s = 0; s < 2; ++s) { const int c0 = s * 4 + hi * 2;
;     const v8i32 a0 = cat8(*reinterpret_cast<const v4i32*>(Kn + KN8SW(r32, c0)), *reinterpret_cast<const v4i32*>(Kn + KN8SW(r32, c0 + 1)));
;     const v8i32 a1 = cat8(*reinterpret_cast<const v4i32*>(Kn + 4096 + KN8SW(r32, c0)), *reinterpret_cast<const v4i32*>(Kn + 4096 + KN8SW(r32, c0 + 1)));
;     p0 = __builtin_amdgcn_mfma_scale_f32_32x32x64_f8f6f4(a0, qf[s], p0, 0, 0, 0, 127, 0, 124);
;     p1 = __builtin_amdgcn_mfma_scale_f32_32x32x64_f8f6f4(a1, qf[s], p1, 0, 0, 0, 127, 0, 124); }
;   { const int c0 = hi * 2;
.Lmla_h2_cont:
	ds_read_b128 v[82:85], v215 offset:24576
	ds_read_b128 v[86:89], v216 offset:24576
	ds_read_b128 v[222:225], v215 offset:28672
	ds_read_b128 v[226:229], v216 offset:28672
	s_add_i32 m0, s98, 0xa800
	s_nop 0
	global_load_lds_dwordx4 v176, s[18:19]
	s_add_i32 m0, s98, 0xc800
	s_nop 0
	global_load_lds_dwordx4 v178, s[16:17]
	s_add_i32 m0, s98, 0xe800
	s_nop 0
	global_load_lds_dwordx4 v[180:181], off
	v_exp_f32_e32 v0, v114
	v_exp_f32_e32 v177, v115
	v_exp_f32_e32 v179, v116
	v_exp_f32_e32 v254, v117
	v_add_f32_e32 v219, v0, v177
	v_cvt_pk_fp8_f32 v246, v0, v177
	v_add_f32_e32 v219, v179, v219
	v_add_f32_e32 v219, v254, v219
	v_cvt_pk_fp8_f32 v246, v179, v254 op_sel:[0,0,1]
	s_waitcnt lgkmcnt(2)
	v_mfma_scale_f32_32x32x64_f8f6f4 v[82:97], v[82:89], v[146:153], v[230:245], v194, v193 op_sel_hi:[0,0,0]
	v_exp_f32_e32 v0, v118
	v_exp_f32_e32 v177, v119
	v_exp_f32_e32 v179, v120
	v_exp_f32_e32 v254, v121
	v_add_f32_e32 v219, v0, v219
	v_add_f32_e32 v219, v177, v219
	v_cvt_pk_fp8_f32 v247, v0, v177
	v_add_f32_e32 v219, v179, v219
	v_add_f32_e32 v219, v254, v219
	v_cvt_pk_fp8_f32 v247, v179, v254 op_sel:[0,0,1]
	ds_read_b128 v[114:117], v213 offset:24576
	ds_read_b128 v[118:121], v214 offset:24576
	s_waitcnt lgkmcnt(2)
	v_mfma_scale_f32_32x32x64_f8f6f4 v[66:81], v[222:229], v[146:153], v[230:245], v194, v193 op_sel_hi:[0,0,0]
	ds_read_b128 v[222:225], v213 offset:28672
	ds_read_b128 v[226:229], v214 offset:28672
	v_exp_f32_e32 v0, v122
	v_exp_f32_e32 v177, v123
	v_exp_f32_e32 v179, v124
	v_exp_f32_e32 v254, v125
	v_add_f32_e32 v219, v0, v219
	v_add_f32_e32 v219, v177, v219
	v_cvt_pk_fp8_f32 v248, v0, v177
	v_add_f32_e32 v219, v179, v219
	v_add_f32_e32 v219, v254, v219
	v_cvt_pk_fp8_f32 v248, v179, v254 op_sel:[0,0,1]
	v_exp_f32_e32 v0, v126
	v_exp_f32_e32 v177, v127
	v_exp_f32_e32 v179, v128
	v_exp_f32_e32 v254, v129
	v_add_f32_e32 v219, v0, v219
	v_add_f32_e32 v219, v177, v219
	v_cvt_pk_fp8_f32 v249, v0, v177
	v_add_f32_e32 v219, v179, v219
	v_add_f32_e32 v219, v254, v219
	v_cvt_pk_fp8_f32 v249, v179, v254 op_sel:[0,0,1]
	ds_read_b128 v[122:125], v185 offset:36864
	ds_read_b128 v[126:129], v186 offset:36864
	s_waitcnt lgkmcnt(4)
	v_mfma_scale_f32_32x32x64_f8f6f4 v[82:97], v[114:121], v[138:145], v[82:97], v194, v193 op_sel_hi:[0,0,0]
	v_exp_f32_e32 v0, v98
	v_exp_f32_e32 v177, v99
	v_exp_f32_e32 v179, v100
	v_exp_f32_e32 v254, v101
	v_add_f32_e32 v219, v0, v219
	v_add_f32_e32 v219, v177, v219
	v_cvt_pk_fp8_f32 v250, v0, v177
	v_add_f32_e32 v219, v179, v219
	v_add_f32_e32 v219, v254, v219
	v_cvt_pk_fp8_f32 v250, v179, v254 op_sel:[0,0,1]
	s_waitcnt lgkmcnt(2)
	v_mfma_scale_f32_32x32x64_f8f6f4 v[66:81], v[222:229], v[138:145], v[66:81], v194, v193 op_sel_hi:[0,0,0]
	ds_read_b128 v[222:225], v185 offset:38912
	ds_read_b128 v[226:229], v186 offset:38912
	v_exp_f32_e32 v0, v102
	v_exp_f32_e32 v177, v103
	v_exp_f32_e32 v179, v104
	v_exp_f32_e32 v254, v105
	v_add_f32_e32 v219, v0, v219
	v_add_f32_e32 v219, v177, v219
	v_cvt_pk_fp8_f32 v251, v0, v177
	v_add_f32_e32 v219, v179, v219
	v_add_f32_e32 v219, v254, v219
	v_cvt_pk_fp8_f32 v251, v179, v254 op_sel:[0,0,1]
	v_exp_f32_e32 v0, v106
	v_exp_f32_e32 v177, v107
	v_exp_f32_e32 v179, v108
	v_exp_f32_e32 v254, v109
	v_add_f32_e32 v219, v0, v219
	v_add_f32_e32 v219, v177, v219
	v_cvt_pk_fp8_f32 v252, v0, v177
	v_add_f32_e32 v219, v179, v219
	v_add_f32_e32 v219, v254, v219
	v_cvt_pk_fp8_f32 v252, v179, v254 op_sel:[0,0,1]
	s_waitcnt lgkmcnt(2)
	v_mfma_scale_f32_32x32x64_f8f6f4 v[82:97], v[122:129], v[130:137], v[82:97], v194, v193 op_sel_hi:[0,0,0]
	v_exp_f32_e32 v0, v110
	v_exp_f32_e32 v177, v111
	v_exp_f32_e32 v179, v112
	v_exp_f32_e32 v254, v113
	v_add_f32_e32 v219, v0, v219
	v_add_f32_e32 v219, v177, v219
	v_cvt_pk_fp8_f32 v253, v0, v177
	v_add_f32_e32 v219, v179, v219
	v_add_f32_e32 v219, v254, v219
	v_cvt_pk_fp8_f32 v253, v179, v254 op_sel:[0,0,1]
	ds_read_b128 v[122:125], v185 offset:0
	ds_read_b128 v[126:129], v186 offset:0
	ds_read_b128 v[114:117], v185 offset:2048
	ds_read_b128 v[118:121], v186 offset:2048
	ds_read_b128 v[106:109], v185 offset:4096
	ds_read_b128 v[110:113], v186 offset:4096
	ds_read_b128 v[98:101], v185 offset:6144
	ds_read_b128 v[102:105], v186 offset:6144
	s_waitcnt lgkmcnt(8)
	v_mfma_scale_f32_32x32x64_f8f6f4 v[66:81], v[222:229], v[130:137], v[66:81], v194, v193 op_sel_hi:[0,0,0]
	v_mov_b32_e32 v0, v219
	s_nop 1
	v_permlane32_swap_b32_e32 v219, v0
	v_add_f32_e32 v219, v219, v0
	v_fma_f32 v209, v209, v221, v219
	v_add_u32_e32 v176, 0x2000, v176
	v_add_u32_e32 v178, 0x20000, v178
	s_mov_b64 s[20:21], 0x1000
	v_lshl_add_u64 v[180:181], v[180:181], 0, s[20:21]
	v_max_f32_e32 v177, v82, v83
	v_max3_f32 v177, v177, v84, v85
	v_max3_f32 v177, v177, v86, v87
	v_max3_f32 v177, v177, v88, v89
	v_max3_f32 v177, v177, v90, v91
	v_max3_f32 v177, v177, v92, v93
	v_max3_f32 v177, v177, v94, v95
	v_max3_f32 v177, v177, v96, v97
	s_waitcnt lgkmcnt(6)
	v_mfma_scale_f32_32x32x64_f8f6f4 v[50:65], v[246:253], v[122:129], v[50:65], v194, v194 op_sel_hi:[0,0,0]
	v_max_f32_e32 v0, v66, v67
	v_max3_f32 v0, v0, v68, v69
	v_max3_f32 v0, v0, v70, v71
	s_waitcnt lgkmcnt(4)
	v_mfma_scale_f32_32x32x64_f8f6f4 v[34:49], v[246:253], v[114:121], v[34:49], v194, v194 op_sel_hi:[0,0,0]
	v_max3_f32 v0, v0, v72, v73
	v_max3_f32 v0, v0, v74, v75
	v_max3_f32 v0, v0, v76, v77
	s_waitcnt lgkmcnt(2)
	v_mfma_scale_f32_32x32x64_f8f6f4 v[18:33], v[246:253], v[106:113], v[18:33], v194, v194 op_sel_hi:[0,0,0]
	v_max3_f32 v0, v0, v78, v79
	v_max3_f32 v0, v0, v80, v81
	v_max_f32_e32 v177, v177, v0
	v_mov_b32_e32 v0, v177
	v_mov_b32_e32 v218, 1.0
	s_waitcnt lgkmcnt(0)
	v_mfma_scale_f32_32x32x64_f8f6f4 v[2:17], v[246:253], v[98:105], v[2:17], v194, v194 op_sel_hi:[0,0,0]
	s_waitcnt vmcnt(0)
	s_waitcnt lgkmcnt(0)
	s_barrier
	v_permlane32_swap_b32_e32 v177, v0
	v_max_f32_e32 v177, v177, v0
	v_cmp_ge_f32_e32 vcc, s90, v177
	s_cmp_eq_u64 vcc, exec
	s_cbranch_scc0 .Lmla_h3_newmax
; __device__ __forceinline__ void finishSM9(f32x16& p0, f32x16& p1, float alpha, float& l_reg, v8i32& p8) {
; #pragma unroll
;   for (int r = 0; r < 16; ++r) { p0[r] = __builtin_amdgcn_exp2f(p0[r]); p1[r] = __builtin_amdgcn_exp2f(p1[r]); }
;   float ps = 0;
; #pragma unroll
;   for (int r = 0; r < 16; ++r) ps += p0[r];
; #pragma unroll
;   for (int r = 0; r < 16; ++r) ps += p1[r];
;   { auto rr = __builtin_amdgcn_permlane32_swap(__float_as_uint(ps), __float_as_uint(ps), false, false);
;     ps = __uint_as_float(rr[0]) + __uint_as_float(rr[1]); }
;   l_reg = l_reg * alpha + ps;
; #pragma unroll
;   for (int g = 0; g < 4; ++g) {
;     int w = __builtin_amdgcn_cvt_pk_fp8_f32(p0[4 * g], p0[4 * g + 1], 0, false); p8[g] = __builtin_amdgcn_cvt_pk_fp8_f32(p0[4 * g + 2], p0[4 * g + 3], w, true);
;     int u = __builtin_amdgcn_cvt_pk_fp8_f32(p1[4 * g], p1[4 * g + 1], 0, false); p8[4 + g] = __builtin_amdgcn_cvt_pk_fp8_f32(p1[4 * g + 2], p1[4 * g + 3], u, true); }
; }
; __device__ __forceinline__ void pv8(f32x16* o, const char* Vt, const v8i32 p8, int r32, int hi) {
;   const int sw = (r32 >> 2) & 3, a0 = r32 * 64 + (((hi * 2) ^ sw) << 4), a1 = r32 * 64 + (((hi * 2 + 1) ^ sw) << 4);
; #pragma unroll
;   for (int d0 = 0; d0 < 4; ++d0) {
;     const v8i32 vf = cat8(*reinterpret_cast<const v4i32*>(Vt + d0 * 2048 + a0), *reinterpret_cast<const v4i32*>(Vt + d0 * 2048 + a1));
;     o[d0] = __builtin_amdgcn_mfma_scale_f32_32x32x64_f8f6f4(p8, vf, o[d0], 0, 0, 0, 127, 0, 127); }
; }
; __device__ __forceinline__ void qkt9(f32x16& p0, f32x16& p1, const char* Kn, const char* Kr, const v8i32* qf, const float init, int r32, int hi) {
; #pragma unroll
;   for (int r = 0; r < 16; ++r) { p0[r] = init; p1[r] = init; }
; #pragma unroll
;   for (int s = 0; s < 2; ++s) { const int c0 = s * 4 + hi * 2;
;     const v8i32 a0 = cat8(*reinterpret_cast<const v4i32*>(Kn + KN8SW(r32, c0)), *reinterpret_cast<const v4i32*>(Kn + KN8SW(r32, c0 + 1)));
;     const v8i32 a1 = cat8(*reinterpret_cast<const v4i32*>(Kn + 4096 + KN8SW(r32, c0)), *reinterpret_cast<const v4i32*>(Kn + 4096 + KN8SW(r32, c0 + 1)));
;     p0 = __builtin_amdgcn_mfma_scale_f32_32x32x64_f8f6f4(a0, qf[s], p0, 0, 0, 0, 127, 0, 124);
;     p1 = __builtin_amdgcn_mfma_scale_f32_32x32x64_f8f6f4(a1, qf[s], p1, 0, 0, 0, 127, 0, 124); }
;   { const int c0 = hi * 2;
.Lmla_h3_cont:
	ds_read_b128 v[114:117], v215 offset:51200
	ds_read_b128 v[118:121], v216 offset:51200
	ds_read_b128 v[222:225], v215 offset:55296
	ds_read_b128 v[226:229], v216 offset:55296
	s_add_i32 m0, s98, 0x0
	s_nop 0
	global_load_lds_dwordx4 v176, s[18:19]
	s_add_i32 m0, s98, 0x4000
	s_nop 0
	global_load_lds_dwordx4 v178, s[16:17]
	s_add_i32 m0, s98, 0x8000
	s_nop 0
	global_load_lds_dwordx4 v[180:181], off
	v_exp_f32_e32 v0, v82
	v_exp_f32_e32 v177, v83
	v_exp_f32_e32 v179, v84
	v_exp_f32_e32 v254, v85
	v_add_f32_e32 v219, v0, v177
	v_cvt_pk_fp8_f32 v246, v0, v177
	v_add_f32_e32 v219, v179, v219
	v_add_f32_e32 v219, v254, v219
	v_cvt_pk_fp8_f32 v246, v179, v254 op_sel:[0,0,1]
	s_waitcnt lgkmcnt(2)
	v_mfma_scale_f32_32x32x64_f8f6f4 v[114:129], v[114:121], v[146:153], v[230:245], v194, v193 op_sel_hi:[0,0,0]
	v_exp_f32_e32 v0, v86
	v_exp_f32_e32 v177, v87
	v_exp_f32_e32 v179, v88
	v_exp_f32_e32 v254, v89
	v_add_f32_e32 v219, v0, v219
	v_add_f32_e32 v219, v177, v219
	v_cvt_pk_fp8_f32 v247, v0, v177
	v_add_f32_e32 v219, v179, v219
	v_add_f32_e32 v219, v254, v219
	v_cvt_pk_fp8_f32 v247, v179, v254 op_sel:[0,0,1]
	ds_read_b128 v[82:85], v213 offset:51200
	ds_read_b128 v[86:89], v214 offset:51200
	s_waitcnt lgkmcnt(2)
	v_mfma_scale_f32_32x32x64_f8f6f4 v[98:113], v[222:229], v[146:153], v[230:245], v194, v193 op_sel_hi:[0,0,0]
	ds_read_b128 v[222:225], v213 offset:55296
	ds_read_b128 v[226:229], v214 offset:55296
	v_exp_f32_e32 v0, v90
	v_exp_f32_e32 v177, v91
	v_exp_f32_e32 v179, v92
	v_exp_f32_e32 v254, v93
	v_add_f32_e32 v219, v0, v219
	v_add_f32_e32 v219, v177, v219
	v_cvt_pk_fp8_f32 v248, v0, v177
	v_add_f32_e32 v219, v179, v219
	v_add_f32_e32 v219, v254, v219
	v_cvt_pk_fp8_f32 v248, v179, v254 op_sel:[0,0,1]
	v_exp_f32_e32 v0, v94
	v_exp_f32_e32 v177, v95
	v_exp_f32_e32 v179, v96
	v_exp_f32_e32 v254, v97
	v_add_f32_e32 v219, v0, v219
	v_add_f32_e32 v219, v177, v219
	v_cvt_pk_fp8_f32 v249, v0, v177
	v_add_f32_e32 v219, v179, v219
	v_add_f32_e32 v219, v254, v219
	v_cvt_pk_fp8_f32 v249, v179, v254 op_sel:[0,0,1]
	ds_read_b128 v[90:93], v185 offset:59392
	ds_read_b128 v[94:97], v186 offset:59392
	s_waitcnt lgkmcnt(4)
	v_mfma_scale_f32_32x32x64_f8f6f4 v[114:129], v[82:89], v[138:145], v[114:129], v194, v193 op_sel_hi:[0,0,0]
	v_exp_f32_e32 v0, v66
	v_exp_f32_e32 v177, v67
	v_exp_f32_e32 v179, v68
	v_exp_f32_e32 v254, v69
	v_add_f32_e32 v219, v0, v219
	v_add_f32_e32 v219, v177, v219
	v_cvt_pk_fp8_f32 v250, v0, v177
	v_add_f32_e32 v219, v179, v219
	v_add_f32_e32 v219, v254, v219
	v_cvt_pk_fp8_f32 v250, v179, v254 op_sel:[0,0,1]
	s_waitcnt lgkmcnt(2)
	v_mfma_scale_f32_32x32x64_f8f6f4 v[98:113], v[222:229], v[138:145], v[98:113], v194, v193 op_sel_hi:[0,0,0]
	ds_read_b128 v[222:225], v185 offset:61440
	ds_read_b128 v[226:229], v186 offset:61440
	v_exp_f32_e32 v0, v70
	v_exp_f32_e32 v177, v71
	v_exp_f32_e32 v179, v72
	v_exp_f32_e32 v254, v73
	v_add_f32_e32 v219, v0, v219
	v_add_f32_e32 v219, v177, v219
	v_cvt_pk_fp8_f32 v251, v0, v177
	v_add_f32_e32 v219, v179, v219
	v_add_f32_e32 v219, v254, v219
	v_cvt_pk_fp8_f32 v251, v179, v254 op_sel:[0,0,1]
	v_exp_f32_e32 v0, v74
	v_exp_f32_e32 v177, v75
	v_exp_f32_e32 v179, v76
	v_exp_f32_e32 v254, v77
	v_add_f32_e32 v219, v0, v219
	v_add_f32_e32 v219, v177, v219
	v_cvt_pk_fp8_f32 v252, v0, v177
	v_add_f32_e32 v219, v179, v219
	v_add_f32_e32 v219, v254, v219
	v_cvt_pk_fp8_f32 v252, v179, v254 op_sel:[0,0,1]
	s_waitcnt lgkmcnt(2)
	v_mfma_scale_f32_32x32x64_f8f6f4 v[114:129], v[90:97], v[130:137], v[114:129], v194, v193 op_sel_hi:[0,0,0]
	v_exp_f32_e32 v0, v78
	v_exp_f32_e32 v177, v79
	v_exp_f32_e32 v179, v80
	v_exp_f32_e32 v254, v81
	v_add_f32_e32 v219, v0, v219
	v_add_f32_e32 v219, v177, v219
	v_cvt_pk_fp8_f32 v253, v0, v177
	v_add_f32_e32 v219, v179, v219
	v_add_f32_e32 v219, v254, v219
	v_cvt_pk_fp8_f32 v253, v179, v254 op_sel:[0,0,1]
	ds_read_b128 v[90:93], v185 offset:8192
	ds_read_b128 v[94:97], v186 offset:8192
	ds_read_b128 v[82:85], v185 offset:10240
	ds_read_b128 v[86:89], v186 offset:10240
	ds_read_b128 v[74:77], v185 offset:12288
	ds_read_b128 v[78:81], v186 offset:12288
	ds_read_b128 v[66:69], v185 offset:14336
	ds_read_b128 v[70:73], v186 offset:14336
	s_waitcnt lgkmcnt(8)
	v_mfma_scale_f32_32x32x64_f8f6f4 v[98:113], v[222:229], v[130:137], v[98:113], v194, v193 op_sel_hi:[0,0,0]
	v_mov_b32_e32 v0, v219
	s_nop 1
	v_permlane32_swap_b32_e32 v219, v0
	v_add_f32_e32 v219, v219, v0
	v_fma_f32 v209, v209, v218, v219
	v_add_u32_e32 v176, 0x2000, v176
	v_add_u32_e32 v178, 0x20000, v178
	s_mov_b64 s[20:21], 0x1000
	v_lshl_add_u64 v[180:181], v[180:181], 0, s[20:21]
	v_max_f32_e32 v177, v114, v115
	v_max3_f32 v177, v177, v116, v117
	v_max3_f32 v177, v177, v118, v119
	v_max3_f32 v177, v177, v120, v121
	v_max3_f32 v177, v177, v122, v123
	v_max3_f32 v177, v177, v124, v125
	v_max3_f32 v177, v177, v126, v127
	v_max3_f32 v177, v177, v128, v129
	s_waitcnt lgkmcnt(6)
	v_mfma_scale_f32_32x32x64_f8f6f4 v[50:65], v[246:253], v[90:97], v[50:65], v194, v194 op_sel_hi:[0,0,0]
	v_max_f32_e32 v0, v98, v99
	v_max3_f32 v0, v0, v100, v101
	v_max3_f32 v0, v0, v102, v103
	s_waitcnt lgkmcnt(4)
	v_mfma_scale_f32_32x32x64_f8f6f4 v[34:49], v[246:253], v[82:89], v[34:49], v194, v194 op_sel_hi:[0,0,0]
	v_max3_f32 v0, v0, v104, v105
	v_max3_f32 v0, v0, v106, v107
	v_max3_f32 v0, v0, v108, v109
	s_waitcnt lgkmcnt(2)
	v_mfma_scale_f32_32x32x64_f8f6f4 v[18:33], v[246:253], v[74:81], v[18:33], v194, v194 op_sel_hi:[0,0,0]
	v_max3_f32 v0, v0, v110, v111
	v_max3_f32 v0, v0, v112, v113
	v_max_f32_e32 v177, v177, v0
	v_mov_b32_e32 v0, v177
	v_mov_b32_e32 v221, 1.0
	s_waitcnt lgkmcnt(0)
	v_mfma_scale_f32_32x32x64_f8f6f4 v[2:17], v[246:253], v[66:73], v[2:17], v194, v194 op_sel_hi:[0,0,0]
	s_waitcnt vmcnt(0)
	s_waitcnt lgkmcnt(0)
	s_barrier
	v_permlane32_swap_b32_e32 v177, v0
	v_max_f32_e32 v177, v177, v0
	v_cmp_ge_f32_e32 vcc, s90, v177
	s_cmp_eq_u64 vcc, exec
	s_cbranch_scc0 .Lmla_h4_newmax
; __device__ __forceinline__ void finishSM9(f32x16& p0, f32x16& p1, float alpha, float& l_reg, v8i32& p8) {
; #pragma unroll
;   for (int r = 0; r < 16; ++r) { p0[r] = __builtin_amdgcn_exp2f(p0[r]); p1[r] = __builtin_amdgcn_exp2f(p1[r]); }
;   float ps = 0;
; #pragma unroll
;   for (int r = 0; r < 16; ++r) ps += p0[r];
; #pragma unroll
;   for (int r = 0; r < 16; ++r) ps += p1[r];
;   { auto rr = __builtin_amdgcn_permlane32_swap(__float_as_uint(ps), __float_as_uint(ps), false, false);
;     ps = __uint_as_float(rr[0]) + __uint_as_float(rr[1]); }
;   l_reg = l_reg * alpha + ps;
; #pragma unroll
;   for (int g = 0; g < 4; ++g) {
;     int w = __builtin_amdgcn_cvt_pk_fp8_f32(p0[4 * g], p0[4 * g + 1], 0, false); p8[g] = __builtin_amdgcn_cvt_pk_fp8_f32(p0[4 * g + 2], p0[4 * g + 3], w, true);
;     int u = __builtin_amdgcn_cvt_pk_fp8_f32(p1[4 * g], p1[4 * g + 1], 0, false); p8[4 + g] = __builtin_amdgcn_cvt_pk_fp8_f32(p1[4 * g + 2], p1[4 * g + 3], u, true); }
; }
; __device__ __forceinline__ void pv8(f32x16* o, const char* Vt, const v8i32 p8, int r32, int hi) {
;   const int sw = (r32 >> 2) & 3, a0 = r32 * 64 + (((hi * 2) ^ sw) << 4), a1 = r32 * 64 + (((hi * 2 + 1) ^ sw) << 4);
; #pragma unroll
;   for (int d0 = 0; d0 < 4; ++d0) {
;     const v8i32 vf = cat8(*reinterpret_cast<const v4i32*>(Vt + d0 * 2048 + a0), *reinterpret_cast<const v4i32*>(Vt + d0 * 2048 + a1));
;     o[d0] = __builtin_amdgcn_mfma_scale_f32_32x32x64_f8f6f4(p8, vf, o[d0], 0, 0, 0, 127, 0, 127); }
; }
; __device__ __forceinline__ void qkt9(f32x16& p0, f32x16& p1, const char* Kn, const char* Kr, const v8i32* qf, const float init, int r32, int hi) {
; #pragma unroll
;   for (int r = 0; r < 16; ++r) { p0[r] = init; p1[r] = init; }
; #pragma unroll
;   for (int s = 0; s < 2; ++s) { const int c0 = s * 4 + hi * 2;
;     const v8i32 a0 = cat8(*reinterpret_cast<const v4i32*>(Kn + KN8SW(r32, c0)), *reinterpret_cast<const v4i32*>(Kn + KN8SW(r32, c0 + 1)));
;     const v8i32 a1 = cat8(*reinterpret_cast<const v4i32*>(Kn + 4096 + KN8SW(r32, c0)), *reinterpret_cast<const v4i32*>(Kn + 4096 + KN8SW(r32, c0 + 1)));
;     p0 = __builtin_amdgcn_mfma_scale_f32_32x32x64_f8f6f4(a0, qf[s], p0, 0, 0, 0, 127, 0, 124);
;     p1 = __builtin_amdgcn_mfma_scale_f32_32x32x64_f8f6f4(a1, qf[s], p1, 0, 0, 0, 127, 0, 124); }
;   { const int c0 = hi * 2;
.Lmla_h4_cont:
	ds_read_b128 v[82:85], v215 offset:16384
	ds_read_b128 v[86:89], v216 offset:16384
	ds_read_b128 v[222:225], v215 offset:20480
	ds_read_b128 v[226:229], v216 offset:20480
	s_add_i32 m0, s98, 0x2000
	s_nop 0
	global_load_lds_dwordx4 v176, s[18:19]
	s_add_i32 m0, s98, 0x6000
	s_nop 0
	global_load_lds_dwordx4 v178, s[16:17]
	s_add_i32 m0, s98, 0x9000
	s_nop 0
	global_load_lds_dwordx4 v[180:181], off
	v_exp_f32_e32 v0, v114
	v_exp_f32_e32 v177, v115
	v_exp_f32_e32 v179, v116
	v_exp_f32_e32 v254, v117
	v_add_f32_e32 v219, v0, v177
	v_cvt_pk_fp8_f32 v246, v0, v177
	v_add_f32_e32 v219, v179, v219
	v_add_f32_e32 v219, v254, v219
	v_cvt_pk_fp8_f32 v246, v179, v254 op_sel:[0,0,1]
	s_waitcnt lgkmcnt(2)
	v_mfma_scale_f32_32x32x64_f8f6f4 v[82:97], v[82:89], v[146:153], v[230:245], v194, v193 op_sel_hi:[0,0,0]
	v_exp_f32_e32 v0, v118
	v_exp_f32_e32 v177, v119
	v_exp_f32_e32 v179, v120
	v_exp_f32_e32 v254, v121
	v_add_f32_e32 v219, v0, v219
	v_add_f32_e32 v219, v177, v219
	v_cvt_pk_fp8_f32 v247, v0, v177
	v_add_f32_e32 v219, v179, v219
	v_add_f32_e32 v219, v254, v219
	v_cvt_pk_fp8_f32 v247, v179, v254 op_sel:[0,0,1]
	ds_read_b128 v[114:117], v213 offset:16384
	ds_read_b128 v[118:121], v214 offset:16384
	s_waitcnt lgkmcnt(2)
	v_mfma_scale_f32_32x32x64_f8f6f4 v[66:81], v[222:229], v[146:153], v[230:245], v194, v193 op_sel_hi:[0,0,0]
	ds_read_b128 v[222:225], v213 offset:20480
	ds_read_b128 v[226:229], v214 offset:20480
	v_exp_f32_e32 v0, v122
	v_exp_f32_e32 v177, v123
	v_exp_f32_e32 v179, v124
	v_exp_f32_e32 v254, v125
	v_add_f32_e32 v219, v0, v219
	v_add_f32_e32 v219, v177, v219
	v_cvt_pk_fp8_f32 v248, v0, v177
	v_add_f32_e32 v219, v179, v219
	v_add_f32_e32 v219, v254, v219
	v_cvt_pk_fp8_f32 v248, v179, v254 op_sel:[0,0,1]
	v_exp_f32_e32 v0, v126
	v_exp_f32_e32 v177, v127
	v_exp_f32_e32 v179, v128
	v_exp_f32_e32 v254, v129
	v_add_f32_e32 v219, v0, v219
	v_add_f32_e32 v219, v177, v219
	v_cvt_pk_fp8_f32 v249, v0, v177
	v_add_f32_e32 v219, v179, v219
	v_add_f32_e32 v219, v254, v219
	v_cvt_pk_fp8_f32 v249, v179, v254 op_sel:[0,0,1]
	ds_read_b128 v[122:125], v185 offset:32768
	ds_read_b128 v[126:129], v186 offset:32768
	s_waitcnt lgkmcnt(4)
	v_mfma_scale_f32_32x32x64_f8f6f4 v[82:97], v[114:121], v[138:145], v[82:97], v194, v193 op_sel_hi:[0,0,0]
	v_exp_f32_e32 v0, v98
	v_exp_f32_e32 v177, v99
	v_exp_f32_e32 v179, v100
	v_exp_f32_e32 v254, v101
	v_add_f32_e32 v219, v0, v219
	v_add_f32_e32 v219, v177, v219
	v_cvt_pk_fp8_f32 v250, v0, v177
	v_add_f32_e32 v219, v179, v219
	v_add_f32_e32 v219, v254, v219
	v_cvt_pk_fp8_f32 v250, v179, v254 op_sel:[0,0,1]
	s_waitcnt lgkmcnt(2)
	v_mfma_scale_f32_32x32x64_f8f6f4 v[66:81], v[222:229], v[138:145], v[66:81], v194, v193 op_sel_hi:[0,0,0]
	ds_read_b128 v[222:225], v185 offset:34816
	ds_read_b128 v[226:229], v186 offset:34816
	v_exp_f32_e32 v0, v102
	v_exp_f32_e32 v177, v103
	v_exp_f32_e32 v179, v104
	v_exp_f32_e32 v254, v105
	v_add_f32_e32 v219, v0, v219
	v_add_f32_e32 v219, v177, v219
	v_cvt_pk_fp8_f32 v251, v0, v177
	v_add_f32_e32 v219, v179, v219
	v_add_f32_e32 v219, v254, v219
	v_cvt_pk_fp8_f32 v251, v179, v254 op_sel:[0,0,1]
	v_exp_f32_e32 v0, v106
	v_exp_f32_e32 v177, v107
	v_exp_f32_e32 v179, v108
	v_exp_f32_e32 v254, v109
	v_add_f32_e32 v219, v0, v219
	v_add_f32_e32 v219, v177, v219
	v_cvt_pk_fp8_f32 v252, v0, v177
	v_add_f32_e32 v219, v179, v219
	v_add_f32_e32 v219, v254, v219
	v_cvt_pk_fp8_f32 v252, v179, v254 op_sel:[0,0,1]
	s_waitcnt lgkmcnt(2)
	v_mfma_scale_f32_32x32x64_f8f6f4 v[82:97], v[122:129], v[130:137], v[82:97], v194, v193 op_sel_hi:[0,0,0]
	v_exp_f32_e32 v0, v110
	v_exp_f32_e32 v177, v111
	v_exp_f32_e32 v179, v112
	v_exp_f32_e32 v254, v113
	v_add_f32_e32 v219, v0, v219
	v_add_f32_e32 v219, v177, v219
	v_cvt_pk_fp8_f32 v253, v0, v177
	v_add_f32_e32 v219, v179, v219
	v_add_f32_e32 v219, v254, v219
	v_cvt_pk_fp8_f32 v253, v179, v254 op_sel:[0,0,1]
	ds_read_b128 v[122:125], v185 offset:43008
	ds_read_b128 v[126:129], v186 offset:43008
	ds_read_b128 v[114:117], v185 offset:45056
	ds_read_b128 v[118:121], v186 offset:45056
	ds_read_b128 v[106:109], v185 offset:47104
	ds_read_b128 v[110:113], v186 offset:47104
	ds_read_b128 v[98:101], v185 offset:49152
	ds_read_b128 v[102:105], v186 offset:49152
	s_waitcnt lgkmcnt(8)
	v_mfma_scale_f32_32x32x64_f8f6f4 v[66:81], v[222:229], v[130:137], v[66:81], v194, v193 op_sel_hi:[0,0,0]
	v_mov_b32_e32 v0, v219
	s_nop 1
	v_permlane32_swap_b32_e32 v219, v0
	v_add_f32_e32 v219, v219, v0
	v_fma_f32 v209, v209, v221, v219
	v_add_u32_e32 v176, 0x2000, v176
	v_add_u32_e32 v178, 0x20000, v178
	s_mov_b64 s[20:21], 0x1000
	v_lshl_add_u64 v[180:181], v[180:181], 0, s[20:21]
	v_max_f32_e32 v177, v82, v83
	v_max3_f32 v177, v177, v84, v85
	v_max3_f32 v177, v177, v86, v87
	v_max3_f32 v177, v177, v88, v89
	v_max3_f32 v177, v177, v90, v91
	v_max3_f32 v177, v177, v92, v93
	v_max3_f32 v177, v177, v94, v95
	v_max3_f32 v177, v177, v96, v97
	s_waitcnt lgkmcnt(6)
	v_mfma_scale_f32_32x32x64_f8f6f4 v[50:65], v[246:253], v[122:129], v[50:65], v194, v194 op_sel_hi:[0,0,0]
	v_max_f32_e32 v0, v66, v67
	v_max3_f32 v0, v0, v68, v69
	v_max3_f32 v0, v0, v70, v71
	s_waitcnt lgkmcnt(4)
	v_mfma_scale_f32_32x32x64_f8f6f4 v[34:49], v[246:253], v[114:121], v[34:49], v194, v194 op_sel_hi:[0,0,0]
	v_max3_f32 v0, v0, v72, v73
	v_max3_f32 v0, v0, v74, v75
	v_max3_f32 v0, v0, v76, v77
	s_waitcnt lgkmcnt(2)
	v_mfma_scale_f32_32x32x64_f8f6f4 v[18:33], v[246:253], v[106:113], v[18:33], v194, v194 op_sel_hi:[0,0,0]
	v_max3_f32 v0, v0, v78, v79
	v_max3_f32 v0, v0, v80, v81
	v_max_f32_e32 v177, v177, v0
	v_mov_b32_e32 v0, v177
	v_mov_b32_e32 v218, 1.0
	s_waitcnt lgkmcnt(0)
	v_mfma_scale_f32_32x32x64_f8f6f4 v[2:17], v[246:253], v[98:105], v[2:17], v194, v194 op_sel_hi:[0,0,0]
	s_waitcnt vmcnt(0)
	s_waitcnt lgkmcnt(0)
	s_barrier
	v_permlane32_swap_b32_e32 v177, v0
	v_max_f32_e32 v177, v177, v0
	v_cmp_ge_f32_e32 vcc, s90, v177
	s_cmp_eq_u64 vcc, exec
	s_cbranch_scc0 .Lmla_h5_newmax
; __device__ __forceinline__ void finishSM9(f32x16& p0, f32x16& p1, float alpha, float& l_reg, v8i32& p8) {
; #pragma unroll
;   for (int r = 0; r < 16; ++r) { p0[r] = __builtin_amdgcn_exp2f(p0[r]); p1[r] = __builtin_amdgcn_exp2f(p1[r]); }
;   float ps = 0;
; #pragma unroll
;   for (int r = 0; r < 16; ++r) ps += p0[r];
; #pragma unroll
;   for (int r = 0; r < 16; ++r) ps += p1[r];
;   { auto rr = __builtin_amdgcn_permlane32_swap(__float_as_uint(ps), __float_as_uint(ps), false, false);
;     ps = __uint_as_float(rr[0]) + __uint_as_float(rr[1]); }
;   l_reg = l_reg * alpha + ps;
; #pragma unroll
;   for (int g = 0; g < 4; ++g) {
;     int w = __builtin_amdgcn_cvt_pk_fp8_f32(p0[4 * g], p0[4 * g + 1], 0, false); p8[g] = __builtin_amdgcn_cvt_pk_fp8_f32(p0[4 * g + 2], p0[4 * g + 3], w, true);
;     int u = __builtin_amdgcn_cvt_pk_fp8_f32(p1[4 * g], p1[4 * g + 1], 0, false); p8[4 + g] = __builtin_amdgcn_cvt_pk_fp8_f32(p1[4 * g + 2], p1[4 * g + 3], u, true); }
; }
; __device__ __forceinline__ void pv8(f32x16* o, const char* Vt, const v8i32 p8, int r32, int hi) {
;   const int sw = (r32 >> 2) & 3, a0 = r32 * 64 + (((hi * 2) ^ sw) << 4), a1 = r32 * 64 + (((hi * 2 + 1) ^ sw) << 4);
; #pragma unroll
;   for (int d0 = 0; d0 < 4; ++d0) {
;     const v8i32 vf = cat8(*reinterpret_cast<const v4i32*>(Vt + d0 * 2048 + a0), *reinterpret_cast<const v4i32*>(Vt + d0 * 2048 + a1));
;     o[d0] = __builtin_amdgcn_mfma_scale_f32_32x32x64_f8f6f4(p8, vf, o[d0], 0, 0, 0, 127, 0, 127); }
; }
; __device__ __forceinline__ void qkt9(f32x16& p0, f32x16& p1, const char* Kn, const char* Kr, const v8i32* qf, const float init, int r32, int hi) {
; #pragma unroll
;   for (int r = 0; r < 16; ++r) { p0[r] = init; p1[r] = init; }
; #pragma unroll
;   for (int s = 0; s < 2; ++s) { const int c0 = s * 4 + hi * 2;
;     const v8i32 a0 = cat8(*reinterpret_cast<const v4i32*>(Kn + KN8SW(r32, c0)), *reinterpret_cast<const v4i32*>(Kn + KN8SW(r32, c0 + 1)));
;     const v8i32 a1 = cat8(*reinterpret_cast<const v4i32*>(Kn + 4096 + KN8SW(r32, c0)), *reinterpret_cast<const v4i32*>(Kn + 4096 + KN8SW(r32, c0 + 1)));
;     p0 = __builtin_amdgcn_mfma_scale_f32_32x32x64_f8f6f4(a0, qf[s], p0, 0, 0, 0, 127, 0, 124);
;     p1 = __builtin_amdgcn_mfma_scale_f32_32x32x64_f8f6f4(a1, qf[s], p1, 0, 0, 0, 127, 0, 124); }
;   { const int c0 = hi * 2;
.Lmla_h5_cont:
	s_add_i32 s30, s30, 1
	s_cmpk_lt_u32 s30, 42
	s_cbranch_scc1 .LBB0_1321
	ds_read_b128 v[114:117], v215 offset:24576
	ds_read_b128 v[118:121], v216 offset:24576
	ds_read_b128 v[222:225], v215 offset:28672
	ds_read_b128 v[226:229], v216 offset:28672
	s_add_i32 m0, s98, 0xa800
	s_nop 0
	global_load_lds_dwordx4 v176, s[18:19]
	s_add_i32 m0, s98, 0xc800
	s_nop 0
	global_load_lds_dwordx4 v178, s[16:17]
	s_add_i32 m0, s98, 0xe800
	s_nop 0
	global_load_lds_dwordx4 v[180:181], off
	v_exp_f32_e32 v0, v82
	v_exp_f32_e32 v177, v83
	v_exp_f32_e32 v179, v84
	v_exp_f32_e32 v254, v85
	v_add_f32_e32 v219, v0, v177
	v_cvt_pk_fp8_f32 v246, v0, v177
	v_add_f32_e32 v219, v179, v219
	v_add_f32_e32 v219, v254, v219
	v_cvt_pk_fp8_f32 v246, v179, v254 op_sel:[0,0,1]
	s_waitcnt lgkmcnt(2)
	v_mfma_scale_f32_32x32x64_f8f6f4 v[114:129], v[114:121], v[146:153], v[230:245], v194, v193 op_sel_hi:[0,0,0]
	v_exp_f32_e32 v0, v86
	v_exp_f32_e32 v177, v87
	v_exp_f32_e32 v179, v88
	v_exp_f32_e32 v254, v89
	v_add_f32_e32 v219, v0, v219
	v_add_f32_e32 v219, v177, v219
	v_cvt_pk_fp8_f32 v247, v0, v177
	v_add_f32_e32 v219, v179, v219
	v_add_f32_e32 v219, v254, v219
	v_cvt_pk_fp8_f32 v247, v179, v254 op_sel:[0,0,1]
	ds_read_b128 v[82:85], v213 offset:24576
	ds_read_b128 v[86:89], v214 offset:24576
	s_waitcnt lgkmcnt(2)
	v_mfma_scale_f32_32x32x64_f8f6f4 v[98:113], v[222:229], v[146:153], v[230:245], v194, v193 op_sel_hi:[0,0,0]
	ds_read_b128 v[222:225], v213 offset:28672
	ds_read_b128 v[226:229], v214 offset:28672
	v_exp_f32_e32 v0, v90
	v_exp_f32_e32 v177, v91
	v_exp_f32_e32 v179, v92
	v_exp_f32_e32 v254, v93
	v_add_f32_e32 v219, v0, v219
	v_add_f32_e32 v219, v177, v219
	v_cvt_pk_fp8_f32 v248, v0, v177
	v_add_f32_e32 v219, v179, v219
	v_add_f32_e32 v219, v254, v219
	v_cvt_pk_fp8_f32 v248, v179, v254 op_sel:[0,0,1]
	v_exp_f32_e32 v0, v94
	v_exp_f32_e32 v177, v95
	v_exp_f32_e32 v179, v96
	v_exp_f32_e32 v254, v97
	v_add_f32_e32 v219, v0, v219
	v_add_f32_e32 v219, v177, v219
	v_cvt_pk_fp8_f32 v249, v0, v177
	v_add_f32_e32 v219, v179, v219
	v_add_f32_e32 v219, v254, v219
	v_cvt_pk_fp8_f32 v249, v179, v254 op_sel:[0,0,1]
	ds_read_b128 v[90:93], v185 offset:36864
	ds_read_b128 v[94:97], v186 offset:36864
	s_waitcnt lgkmcnt(4)
	v_mfma_scale_f32_32x32x64_f8f6f4 v[114:129], v[82:89], v[138:145], v[114:129], v194, v193 op_sel_hi:[0,0,0]
	v_exp_f32_e32 v0, v66
	v_exp_f32_e32 v177, v67
	v_exp_f32_e32 v179, v68
	v_exp_f32_e32 v254, v69
	v_add_f32_e32 v219, v0, v219
	v_add_f32_e32 v219, v177, v219
	v_cvt_pk_fp8_f32 v250, v0, v177
	v_add_f32_e32 v219, v179, v219
	v_add_f32_e32 v219, v254, v219
	v_cvt_pk_fp8_f32 v250, v179, v254 op_sel:[0,0,1]
	s_waitcnt lgkmcnt(2)
	v_mfma_scale_f32_32x32x64_f8f6f4 v[98:113], v[222:229], v[138:145], v[98:113], v194, v193 op_sel_hi:[0,0,0]
	ds_read_b128 v[222:225], v185 offset:38912
	ds_read_b128 v[226:229], v186 offset:38912
	v_exp_f32_e32 v0, v70
	v_exp_f32_e32 v177, v71
	v_exp_f32_e32 v179, v72
	v_exp_f32_e32 v254, v73
	v_add_f32_e32 v219, v0, v219
	v_add_f32_e32 v219, v177, v219
	v_cvt_pk_fp8_f32 v251, v0, v177
	v_add_f32_e32 v219, v179, v219
	v_add_f32_e32 v219, v254, v219
	v_cvt_pk_fp8_f32 v251, v179, v254 op_sel:[0,0,1]
	v_exp_f32_e32 v0, v74
	v_exp_f32_e32 v177, v75
	v_exp_f32_e32 v179, v76
	v_exp_f32_e32 v254, v77
	v_add_f32_e32 v219, v0, v219
	v_add_f32_e32 v219, v177, v219
	v_cvt_pk_fp8_f32 v252, v0, v177
	v_add_f32_e32 v219, v179, v219
	v_add_f32_e32 v219, v254, v219
	v_cvt_pk_fp8_f32 v252, v179, v254 op_sel:[0,0,1]
	s_waitcnt lgkmcnt(2)
	v_mfma_scale_f32_32x32x64_f8f6f4 v[114:129], v[90:97], v[130:137], v[114:129], v194, v193 op_sel_hi:[0,0,0]
	v_exp_f32_e32 v0, v78
	v_exp_f32_e32 v177, v79
	v_exp_f32_e32 v179, v80
	v_exp_f32_e32 v254, v81
	v_add_f32_e32 v219, v0, v219
	v_add_f32_e32 v219, v177, v219
	v_cvt_pk_fp8_f32 v253, v0, v177
	v_add_f32_e32 v219, v179, v219
	v_add_f32_e32 v219, v254, v219
	v_cvt_pk_fp8_f32 v253, v179, v254 op_sel:[0,0,1]
	ds_read_b128 v[90:93], v185 offset:0
	ds_read_b128 v[94:97], v186 offset:0
	ds_read_b128 v[82:85], v185 offset:2048
	ds_read_b128 v[86:89], v186 offset:2048
	ds_read_b128 v[74:77], v185 offset:4096
	ds_read_b128 v[78:81], v186 offset:4096
	ds_read_b128 v[66:69], v185 offset:6144
	ds_read_b128 v[70:73], v186 offset:6144
	s_waitcnt lgkmcnt(8)
	v_mfma_scale_f32_32x32x64_f8f6f4 v[98:113], v[222:229], v[130:137], v[98:113], v194, v193 op_sel_hi:[0,0,0]
	v_mov_b32_e32 v0, v219
	s_nop 1
	v_permlane32_swap_b32_e32 v219, v0
	v_add_f32_e32 v219, v219, v0
	v_fma_f32 v209, v209, v218, v219
	v_add_u32_e32 v176, 0x2000, v176
	v_add_u32_e32 v178, 0x20000, v178
	s_mov_b64 s[20:21], 0x1000
	v_lshl_add_u64 v[180:181], v[180:181], 0, s[20:21]
	v_max_f32_e32 v177, v114, v115
	v_max3_f32 v177, v177, v116, v117
	v_max3_f32 v177, v177, v118, v119
	v_max3_f32 v177, v177, v120, v121
	v_max3_f32 v177, v177, v122, v123
	v_max3_f32 v177, v177, v124, v125
	v_max3_f32 v177, v177, v126, v127
	v_max3_f32 v177, v177, v128, v129
	s_waitcnt lgkmcnt(6)
	v_mfma_scale_f32_32x32x64_f8f6f4 v[50:65], v[246:253], v[90:97], v[50:65], v194, v194 op_sel_hi:[0,0,0]
	v_max_f32_e32 v0, v98, v99
	v_max3_f32 v0, v0, v100, v101
	v_max3_f32 v0, v0, v102, v103
	s_waitcnt lgkmcnt(4)
	v_mfma_scale_f32_32x32x64_f8f6f4 v[34:49], v[246:253], v[82:89], v[34:49], v194, v194 op_sel_hi:[0,0,0]
	v_max3_f32 v0, v0, v104, v105
	v_max3_f32 v0, v0, v106, v107
	v_max3_f32 v0, v0, v108, v109
	s_waitcnt lgkmcnt(2)
	v_mfma_scale_f32_32x32x64_f8f6f4 v[18:33], v[246:253], v[74:81], v[18:33], v194, v194 op_sel_hi:[0,0,0]
	v_max3_f32 v0, v0, v110, v111
	v_max3_f32 v0, v0, v112, v113
	v_max_f32_e32 v177, v177, v0
	v_mov_b32_e32 v0, v177
	v_mov_b32_e32 v221, 1.0
	s_waitcnt lgkmcnt(0)
	v_mfma_scale_f32_32x32x64_f8f6f4 v[2:17], v[246:253], v[66:73], v[2:17], v194, v194 op_sel_hi:[0,0,0]
	s_waitcnt vmcnt(0)
	s_waitcnt lgkmcnt(0)
	s_barrier
	v_permlane32_swap_b32_e32 v177, v0
	v_max_f32_e32 v177, v177, v0
	v_cmp_ge_f32_e32 vcc, s90, v177
	s_cmp_eq_u64 vcc, exec
	s_cbranch_scc0 .Lmla_p0_newmax

; __device__ __forceinline__ void finishSM9(f32x16& p0, f32x16& p1, float alpha, float& l_reg, v8i32& p8) {
; #pragma unroll
;   for (int r = 0; r < 16; ++r) { p0[r] = __builtin_amdgcn_exp2f(p0[r]); p1[r] = __builtin_amdgcn_exp2f(p1[r]); }
;   float ps = 0;
; #pragma unroll
;   for (int r = 0; r < 16; ++r) ps += p0[r];
; #pragma unroll
;   for (int r = 0; r < 16; ++r) ps += p1[r];
;   { auto rr = __builtin_amdgcn_permlane32_swap(__float_as_uint(ps), __float_as_uint(ps), false, false);
;     ps = __uint_as_float(rr[0]) + __uint_as_float(rr[1]); }
;   l_reg = l_reg * alpha + ps;
; #pragma unroll
;   for (int g = 0; g < 4; ++g) {
;     int w = __builtin_amdgcn_cvt_pk_fp8_f32(p0[4 * g], p0[4 * g + 1], 0, false); p8[g] = __builtin_amdgcn_cvt_pk_fp8_f32(p0[4 * g + 2], p0[4 * g + 3], w, true);
;     int u = __builtin_amdgcn_cvt_pk_fp8_f32(p1[4 * g], p1[4 * g + 1], 0, false); p8[4 + g] = __builtin_amdgcn_cvt_pk_fp8_f32(p1[4 * g + 2], p1[4 * g + 3], u, true); }
; }
; __device__ __forceinline__ void pv8(f32x16* o, const char* Vt, const v8i32 p8, int r32, int hi) {
;   const int sw = (r32 >> 2) & 3, a0 = r32 * 64 + (((hi * 2) ^ sw) << 4), a1 = r32 * 64 + (((hi * 2 + 1) ^ sw) << 4);
; #pragma unroll
;   for (int d0 = 0; d0 < 4; ++d0) {
;     const v8i32 vf = cat8(*reinterpret_cast<const v4i32*>(Vt + d0 * 2048 + a0), *reinterpret_cast<const v4i32*>(Vt + d0 * 2048 + a1));
;     o[d0] = __builtin_amdgcn_mfma_scale_f32_32x32x64_f8f6f4(p8, vf, o[d0], 0, 0, 0, 127, 0, 127); }
; }
; __device__ __forceinline__ void qkt9(f32x16& p0, f32x16& p1, const char* Kn, const char* Kr, const v8i32* qf, const float init, int r32, int hi) {
; #pragma unroll
;   for (int r = 0; r < 16; ++r) { p0[r] = init; p1[r] = init; }
; #pragma unroll
;   for (int s = 0; s < 2; ++s) { const int c0 = s * 4 + hi * 2;
;     const v8i32 a0 = cat8(*reinterpret_cast<const v4i32*>(Kn + KN8SW(r32, c0)), *reinterpret_cast<const v4i32*>(Kn + KN8SW(r32, c0 + 1)));
;     const v8i32 a1 = cat8(*reinterpret_cast<const v4i32*>(Kn + 4096 + KN8SW(r32, c0)), *reinterpret_cast<const v4i32*>(Kn + 4096 + KN8SW(r32, c0 + 1)));
;     p0 = __builtin_amdgcn_mfma_scale_f32_32x32x64_f8f6f4(a0, qf[s], p0, 0, 0, 0, 127, 0, 124);
;     p1 = __builtin_amdgcn_mfma_scale_f32_32x32x64_f8f6f4(a1, qf[s], p1, 0, 0, 0, 127, 0, 124); }
;   { const int c0 = hi * 2;
.Lmla_stag_loop:
	ds_read_b128 v[114:117], v215 offset:24576
	ds_read_b128 v[118:121], v216 offset:24576
	ds_read_b128 v[222:225], v215 offset:28672
	ds_read_b128 v[226:229], v216 offset:28672
	v_exp_f32_e32 v0, v82
	v_exp_f32_e32 v177, v83
	v_exp_f32_e32 v179, v84
	v_exp_f32_e32 v254, v85
	v_add_f32_e32 v219, v0, v177
	v_cvt_pk_fp8_f32 v246, v0, v177
	v_add_f32_e32 v219, v179, v219
	v_add_f32_e32 v219, v254, v219
	v_cvt_pk_fp8_f32 v246, v179, v254 op_sel:[0,0,1]
	s_waitcnt lgkmcnt(2)
	v_mfma_scale_f32_32x32x64_f8f6f4 v[114:129], v[114:121], v[146:153], v[230:245], v194, v193 op_sel_hi:[0,0,0]
	v_exp_f32_e32 v0, v86
	v_exp_f32_e32 v177, v87
	v_exp_f32_e32 v179, v88
	v_exp_f32_e32 v254, v89
	v_add_f32_e32 v219, v0, v219
	v_add_f32_e32 v219, v177, v219
	v_cvt_pk_fp8_f32 v247, v0, v177
	v_add_f32_e32 v219, v179, v219
	v_add_f32_e32 v219, v254, v219
	v_cvt_pk_fp8_f32 v247, v179, v254 op_sel:[0,0,1]
	ds_read_b128 v[82:85], v213 offset:24576
	ds_read_b128 v[86:89], v214 offset:24576
	s_waitcnt lgkmcnt(2)
	v_mfma_scale_f32_32x32x64_f8f6f4 v[98:113], v[222:229], v[146:153], v[230:245], v194, v193 op_sel_hi:[0,0,0]
	ds_read_b128 v[222:225], v213 offset:28672
	ds_read_b128 v[226:229], v214 offset:28672
	v_exp_f32_e32 v0, v90
	v_exp_f32_e32 v177, v91
	v_exp_f32_e32 v179, v92
	v_exp_f32_e32 v254, v93
	v_add_f32_e32 v219, v0, v219
	v_add_f32_e32 v219, v177, v219
	v_cvt_pk_fp8_f32 v248, v0, v177
	v_add_f32_e32 v219, v179, v219
	v_add_f32_e32 v219, v254, v219
	v_cvt_pk_fp8_f32 v248, v179, v254 op_sel:[0,0,1]
	v_exp_f32_e32 v0, v94
	v_exp_f32_e32 v177, v95
	v_exp_f32_e32 v179, v96
	v_exp_f32_e32 v254, v97
	v_add_f32_e32 v219, v0, v219
	v_add_f32_e32 v219, v177, v219
	v_cvt_pk_fp8_f32 v249, v0, v177
	v_add_f32_e32 v219, v179, v219
	v_add_f32_e32 v219, v254, v219
	v_cvt_pk_fp8_f32 v249, v179, v254 op_sel:[0,0,1]
	ds_read_b128 v[90:93], v185 offset:36864
	ds_read_b128 v[94:97], v186 offset:36864
	s_waitcnt lgkmcnt(4)
	v_mfma_scale_f32_32x32x64_f8f6f4 v[114:129], v[82:89], v[138:145], v[114:129], v194, v193 op_sel_hi:[0,0,0]
	v_exp_f32_e32 v0, v66
	v_exp_f32_e32 v177, v67
	v_exp_f32_e32 v179, v68
	v_exp_f32_e32 v254, v69
	v_add_f32_e32 v219, v0, v219
	v_add_f32_e32 v219, v177, v219
	v_cvt_pk_fp8_f32 v250, v0, v177
	v_add_f32_e32 v219, v179, v219
	v_add_f32_e32 v219, v254, v219
	v_cvt_pk_fp8_f32 v250, v179, v254 op_sel:[0,0,1]
	s_waitcnt lgkmcnt(2)
	v_mfma_scale_f32_32x32x64_f8f6f4 v[98:113], v[222:229], v[138:145], v[98:113], v194, v193 op_sel_hi:[0,0,0]
	ds_read_b128 v[222:225], v185 offset:38912
	ds_read_b128 v[226:229], v186 offset:38912
	v_exp_f32_e32 v0, v70
	v_exp_f32_e32 v177, v71
	v_exp_f32_e32 v179, v72
	v_exp_f32_e32 v254, v73
	v_add_f32_e32 v219, v0, v219
	v_add_f32_e32 v219, v177, v219
	v_cvt_pk_fp8_f32 v251, v0, v177
	v_add_f32_e32 v219, v179, v219
	v_add_f32_e32 v219, v254, v219
	v_cvt_pk_fp8_f32 v251, v179, v254 op_sel:[0,0,1]
	v_exp_f32_e32 v0, v74
	v_exp_f32_e32 v177, v75
	v_exp_f32_e32 v179, v76
	v_exp_f32_e32 v254, v77
	v_add_f32_e32 v219, v0, v219
	v_add_f32_e32 v219, v177, v219
	v_cvt_pk_fp8_f32 v252, v0, v177
	v_add_f32_e32 v219, v179, v219
	v_add_f32_e32 v219, v254, v219
	v_cvt_pk_fp8_f32 v252, v179, v254 op_sel:[0,0,1]
	s_waitcnt lgkmcnt(2)
	v_mfma_scale_f32_32x32x64_f8f6f4 v[114:129], v[90:97], v[130:137], v[114:129], v194, v193 op_sel_hi:[0,0,0]
	v_exp_f32_e32 v0, v78
	v_exp_f32_e32 v177, v79
	v_exp_f32_e32 v179, v80
	v_exp_f32_e32 v254, v81
	v_add_f32_e32 v219, v0, v219
	v_add_f32_e32 v219, v177, v219
	v_cvt_pk_fp8_f32 v253, v0, v177
	v_add_f32_e32 v219, v179, v219
	v_add_f32_e32 v219, v254, v219
	v_cvt_pk_fp8_f32 v253, v179, v254 op_sel:[0,0,1]
	ds_read_b128 v[90:93], v185 offset:0
	ds_read_b128 v[94:97], v186 offset:0
	ds_read_b128 v[82:85], v185 offset:2048
	ds_read_b128 v[86:89], v186 offset:2048
	ds_read_b128 v[74:77], v185 offset:4096
	ds_read_b128 v[78:81], v186 offset:4096
	ds_read_b128 v[66:69], v185 offset:6144
	ds_read_b128 v[70:73], v186 offset:6144
	s_waitcnt lgkmcnt(8)
	v_mfma_scale_f32_32x32x64_f8f6f4 v[98:113], v[222:229], v[130:137], v[98:113], v194, v193 op_sel_hi:[0,0,0]
	v_mov_b32_e32 v0, v219
	s_nop 1
	v_permlane32_swap_b32_e32 v219, v0
	v_add_f32_e32 v219, v219, v0
	v_fma_f32 v209, v209, v218, v219
	v_max_f32_e32 v177, v114, v115
	v_max3_f32 v177, v177, v116, v117
	v_max3_f32 v177, v177, v118, v119
	v_max3_f32 v177, v177, v120, v121
	v_max3_f32 v177, v177, v122, v123
	v_max3_f32 v177, v177, v124, v125
	v_max3_f32 v177, v177, v126, v127
	v_max3_f32 v177, v177, v128, v129
	s_waitcnt lgkmcnt(6)
	v_mfma_scale_f32_32x32x64_f8f6f4 v[50:65], v[246:253], v[90:97], v[50:65], v194, v194 op_sel_hi:[0,0,0]
	s_waitcnt lgkmcnt(4)
	v_mfma_scale_f32_32x32x64_f8f6f4 v[34:49], v[246:253], v[82:89], v[34:49], v194, v194 op_sel_hi:[0,0,0]
	s_waitcnt vmcnt(0)
	s_waitcnt lgkmcnt(0)
	s_barrier
	v_max_f32_e32 v0, v98, v99
	v_max3_f32 v0, v0, v100, v101
	v_max3_f32 v0, v0, v102, v103
	v_max3_f32 v0, v0, v104, v105
	s_waitcnt lgkmcnt(2)
	v_mfma_scale_f32_32x32x64_f8f6f4 v[18:33], v[246:253], v[74:81], v[18:33], v194, v194 op_sel_hi:[0,0,0]
	s_add_i32 m0, s98, 0x0
	s_nop 0
	global_load_lds_dwordx4 v176, s[18:19]
	s_add_i32 m0, s98, 0x4000
	s_nop 0
	global_load_lds_dwordx4 v178, s[16:17]
	v_add_u32_e32 v176, 0x2000, v176
	v_add_u32_e32 v178, 0x20000, v178
	v_max3_f32 v0, v0, v106, v107
	v_max3_f32 v0, v0, v108, v109
	v_max3_f32 v0, v0, v110, v111
	v_max3_f32 v0, v0, v112, v113
	s_waitcnt lgkmcnt(0)
	v_mfma_scale_f32_32x32x64_f8f6f4 v[2:17], v[246:253], v[66:73], v[2:17], v194, v194 op_sel_hi:[0,0,0]
	v_max_f32_e32 v177, v177, v0
	v_mov_b32_e32 v0, v177
	v_mov_b32_e32 v221, 1.0
	s_nop 0
	v_permlane32_swap_b32_e32 v177, v0
	v_max_f32_e32 v177, v177, v0
	v_cmp_ge_f32_e32 vcc, s90, v177
	s_cmp_eq_u64 vcc, exec
	s_cbranch_scc0 .Lmla_s0_newmax
; __device__ __forceinline__ void finishSM9(f32x16& p0, f32x16& p1, float alpha, float& l_reg, v8i32& p8) {
; #pragma unroll
;   for (int r = 0; r < 16; ++r) { p0[r] = __builtin_amdgcn_exp2f(p0[r]); p1[r] = __builtin_amdgcn_exp2f(p1[r]); }
;   float ps = 0;
; #pragma unroll
;   for (int r = 0; r < 16; ++r) ps += p0[r];
; #pragma unroll
;   for (int r = 0; r < 16; ++r) ps += p1[r];
;   { auto rr = __builtin_amdgcn_permlane32_swap(__float_as_uint(ps), __float_as_uint(ps), false, false);
;     ps = __uint_as_float(rr[0]) + __uint_as_float(rr[1]); }
;   l_reg = l_reg * alpha + ps;
; #pragma unroll
;   for (int g = 0; g < 4; ++g) {
;     int w = __builtin_amdgcn_cvt_pk_fp8_f32(p0[4 * g], p0[4 * g + 1], 0, false); p8[g] = __builtin_amdgcn_cvt_pk_fp8_f32(p0[4 * g + 2], p0[4 * g + 3], w, true);
;     int u = __builtin_amdgcn_cvt_pk_fp8_f32(p1[4 * g], p1[4 * g + 1], 0, false); p8[4 + g] = __builtin_amdgcn_cvt_pk_fp8_f32(p1[4 * g + 2], p1[4 * g + 3], u, true); }
; }
; __device__ __forceinline__ void pv8(f32x16* o, const char* Vt, const v8i32 p8, int r32, int hi) {
;   const int sw = (r32 >> 2) & 3, a0 = r32 * 64 + (((hi * 2) ^ sw) << 4), a1 = r32 * 64 + (((hi * 2 + 1) ^ sw) << 4);
; #pragma unroll
;   for (int d0 = 0; d0 < 4; ++d0) {
;     const v8i32 vf = cat8(*reinterpret_cast<const v4i32*>(Vt + d0 * 2048 + a0), *reinterpret_cast<const v4i32*>(Vt + d0 * 2048 + a1));
;     o[d0] = __builtin_amdgcn_mfma_scale_f32_32x32x64_f8f6f4(p8, vf, o[d0], 0, 0, 0, 127, 0, 127); }
; }
; __device__ __forceinline__ void qkt9(f32x16& p0, f32x16& p1, const char* Kn, const char* Kr, const v8i32* qf, const float init, int r32, int hi) {
; #pragma unroll
;   for (int r = 0; r < 16; ++r) { p0[r] = init; p1[r] = init; }
; #pragma unroll
;   for (int s = 0; s < 2; ++s) { const int c0 = s * 4 + hi * 2;
;     const v8i32 a0 = cat8(*reinterpret_cast<const v4i32*>(Kn + KN8SW(r32, c0)), *reinterpret_cast<const v4i32*>(Kn + KN8SW(r32, c0 + 1)));
;     const v8i32 a1 = cat8(*reinterpret_cast<const v4i32*>(Kn + 4096 + KN8SW(r32, c0)), *reinterpret_cast<const v4i32*>(Kn + 4096 + KN8SW(r32, c0 + 1)));
;     p0 = __builtin_amdgcn_mfma_scale_f32_32x32x64_f8f6f4(a0, qf[s], p0, 0, 0, 0, 127, 0, 124);
;     p1 = __builtin_amdgcn_mfma_scale_f32_32x32x64_f8f6f4(a1, qf[s], p1, 0, 0, 0, 127, 0, 124); }
;   { const int c0 = hi * 2;
.Lmla_s0_cont:
	ds_read_b128 v[82:85], v215 offset:51200
	ds_read_b128 v[86:89], v216 offset:51200
	ds_read_b128 v[222:225], v215 offset:55296
	ds_read_b128 v[226:229], v216 offset:55296
	v_exp_f32_e32 v0, v114
	v_exp_f32_e32 v177, v115
	v_exp_f32_e32 v179, v116
	v_exp_f32_e32 v254, v117
	v_add_f32_e32 v219, v0, v177
	v_cvt_pk_fp8_f32 v246, v0, v177
	v_add_f32_e32 v219, v179, v219
	v_add_f32_e32 v219, v254, v219
	v_cvt_pk_fp8_f32 v246, v179, v254 op_sel:[0,0,1]
	s_waitcnt lgkmcnt(2)
	v_mfma_scale_f32_32x32x64_f8f6f4 v[82:97], v[82:89], v[146:153], v[230:245], v194, v193 op_sel_hi:[0,0,0]
	v_exp_f32_e32 v0, v118
	v_exp_f32_e32 v177, v119
	v_exp_f32_e32 v179, v120
	v_exp_f32_e32 v254, v121
	v_add_f32_e32 v219, v0, v219
	v_add_f32_e32 v219, v177, v219
	v_cvt_pk_fp8_f32 v247, v0, v177
	v_add_f32_e32 v219, v179, v219
	v_add_f32_e32 v219, v254, v219
	v_cvt_pk_fp8_f32 v247, v179, v254 op_sel:[0,0,1]
	ds_read_b128 v[114:117], v213 offset:51200
	ds_read_b128 v[118:121], v214 offset:51200
	s_waitcnt lgkmcnt(2)
	v_mfma_scale_f32_32x32x64_f8f6f4 v[66:81], v[222:229], v[146:153], v[230:245], v194, v193 op_sel_hi:[0,0,0]
	ds_read_b128 v[222:225], v213 offset:55296
	ds_read_b128 v[226:229], v214 offset:55296
	v_exp_f32_e32 v0, v122
	v_exp_f32_e32 v177, v123
	v_exp_f32_e32 v179, v124
	v_exp_f32_e32 v254, v125
	v_add_f32_e32 v219, v0, v219
	v_add_f32_e32 v219, v177, v219
	v_cvt_pk_fp8_f32 v248, v0, v177
	v_add_f32_e32 v219, v179, v219
	v_add_f32_e32 v219, v254, v219
	v_cvt_pk_fp8_f32 v248, v179, v254 op_sel:[0,0,1]
	v_exp_f32_e32 v0, v126
	v_exp_f32_e32 v177, v127
	v_exp_f32_e32 v179, v128
	v_exp_f32_e32 v254, v129
	v_add_f32_e32 v219, v0, v219
	v_add_f32_e32 v219, v177, v219
	v_cvt_pk_fp8_f32 v249, v0, v177
	v_add_f32_e32 v219, v179, v219
	v_add_f32_e32 v219, v254, v219
	v_cvt_pk_fp8_f32 v249, v179, v254 op_sel:[0,0,1]
	ds_read_b128 v[122:125], v185 offset:59392
	ds_read_b128 v[126:129], v186 offset:59392
	s_waitcnt lgkmcnt(4)
	v_mfma_scale_f32_32x32x64_f8f6f4 v[82:97], v[114:121], v[138:145], v[82:97], v194, v193 op_sel_hi:[0,0,0]
	v_exp_f32_e32 v0, v98
	v_exp_f32_e32 v177, v99
	v_exp_f32_e32 v179, v100
	v_exp_f32_e32 v254, v101
	v_add_f32_e32 v219, v0, v219
	v_add_f32_e32 v219, v177, v219
	v_cvt_pk_fp8_f32 v250, v0, v177
	v_add_f32_e32 v219, v179, v219
	v_add_f32_e32 v219, v254, v219
	v_cvt_pk_fp8_f32 v250, v179, v254 op_sel:[0,0,1]
	s_waitcnt lgkmcnt(2)
	v_mfma_scale_f32_32x32x64_f8f6f4 v[66:81], v[222:229], v[138:145], v[66:81], v194, v193 op_sel_hi:[0,0,0]
	ds_read_b128 v[222:225], v185 offset:61440
	ds_read_b128 v[226:229], v186 offset:61440
	v_exp_f32_e32 v0, v102
	v_exp_f32_e32 v177, v103
	v_exp_f32_e32 v179, v104
	v_exp_f32_e32 v254, v105
	v_add_f32_e32 v219, v0, v219
	v_add_f32_e32 v219, v177, v219
	v_cvt_pk_fp8_f32 v251, v0, v177
	v_add_f32_e32 v219, v179, v219
	v_add_f32_e32 v219, v254, v219
	v_cvt_pk_fp8_f32 v251, v179, v254 op_sel:[0,0,1]
	v_exp_f32_e32 v0, v106
	v_exp_f32_e32 v177, v107
	v_exp_f32_e32 v179, v108
	v_exp_f32_e32 v254, v109
	v_add_f32_e32 v219, v0, v219
	v_add_f32_e32 v219, v177, v219
	v_cvt_pk_fp8_f32 v252, v0, v177
	v_add_f32_e32 v219, v179, v219
	v_add_f32_e32 v219, v254, v219
	v_cvt_pk_fp8_f32 v252, v179, v254 op_sel:[0,0,1]
	s_waitcnt lgkmcnt(2)
	v_mfma_scale_f32_32x32x64_f8f6f4 v[82:97], v[122:129], v[130:137], v[82:97], v194, v193 op_sel_hi:[0,0,0]
	v_exp_f32_e32 v0, v110
	v_exp_f32_e32 v177, v111
	v_exp_f32_e32 v179, v112
	v_exp_f32_e32 v254, v113
	v_add_f32_e32 v219, v0, v219
	v_add_f32_e32 v219, v177, v219
	v_cvt_pk_fp8_f32 v253, v0, v177
	v_add_f32_e32 v219, v179, v219
	v_add_f32_e32 v219, v254, v219
	v_cvt_pk_fp8_f32 v253, v179, v254 op_sel:[0,0,1]
	ds_read_b128 v[122:125], v185 offset:8192
	ds_read_b128 v[126:129], v186 offset:8192
	ds_read_b128 v[114:117], v185 offset:10240
	ds_read_b128 v[118:121], v186 offset:10240
	ds_read_b128 v[106:109], v185 offset:12288
	ds_read_b128 v[110:113], v186 offset:12288
	ds_read_b128 v[98:101], v185 offset:14336
	ds_read_b128 v[102:105], v186 offset:14336
	s_waitcnt lgkmcnt(8)
	v_mfma_scale_f32_32x32x64_f8f6f4 v[66:81], v[222:229], v[130:137], v[66:81], v194, v193 op_sel_hi:[0,0,0]
	v_mov_b32_e32 v0, v219
	s_nop 1
	v_permlane32_swap_b32_e32 v219, v0
	v_add_f32_e32 v219, v219, v0
	v_fma_f32 v209, v209, v221, v219
	v_max_f32_e32 v177, v82, v83
	v_max3_f32 v177, v177, v84, v85
	v_max3_f32 v177, v177, v86, v87
	v_max3_f32 v177, v177, v88, v89
	v_max3_f32 v177, v177, v90, v91
	v_max3_f32 v177, v177, v92, v93
	v_max3_f32 v177, v177, v94, v95
	v_max3_f32 v177, v177, v96, v97
	s_waitcnt lgkmcnt(6)
	v_mfma_scale_f32_32x32x64_f8f6f4 v[50:65], v[246:253], v[122:129], v[50:65], v194, v194 op_sel_hi:[0,0,0]
	s_waitcnt lgkmcnt(4)
	v_mfma_scale_f32_32x32x64_f8f6f4 v[34:49], v[246:253], v[114:121], v[34:49], v194, v194 op_sel_hi:[0,0,0]
	s_waitcnt vmcnt(0)
	s_waitcnt lgkmcnt(0)
	s_barrier
	v_max_f32_e32 v0, v66, v67
	v_max3_f32 v0, v0, v68, v69
	v_max3_f32 v0, v0, v70, v71
	v_max3_f32 v0, v0, v72, v73
	s_waitcnt lgkmcnt(2)
	v_mfma_scale_f32_32x32x64_f8f6f4 v[18:33], v[246:253], v[106:113], v[18:33], v194, v194 op_sel_hi:[0,0,0]
	s_add_i32 m0, s98, 0x2000
	s_nop 0
	global_load_lds_dwordx4 v176, s[18:19]
	s_add_i32 m0, s98, 0x6000
	s_nop 0
	global_load_lds_dwordx4 v178, s[16:17]
	v_add_u32_e32 v176, 0x2000, v176
	v_add_u32_e32 v178, 0x20000, v178
	v_max3_f32 v0, v0, v74, v75
	v_max3_f32 v0, v0, v76, v77
	v_max3_f32 v0, v0, v78, v79
	v_max3_f32 v0, v0, v80, v81
	s_waitcnt lgkmcnt(0)
	v_mfma_scale_f32_32x32x64_f8f6f4 v[2:17], v[246:253], v[98:105], v[2:17], v194, v194 op_sel_hi:[0,0,0]
	v_max_f32_e32 v177, v177, v0
	v_mov_b32_e32 v0, v177
	v_mov_b32_e32 v218, 1.0
	s_nop 0
	v_permlane32_swap_b32_e32 v177, v0
	v_max_f32_e32 v177, v177, v0
	v_cmp_ge_f32_e32 vcc, s90, v177
	s_cmp_eq_u64 vcc, exec
	s_cbranch_scc0 .Lmla_s1_newmax
; __device__ __forceinline__ void finishSM9(f32x16& p0, f32x16& p1, float alpha, float& l_reg, v8i32& p8) {
; #pragma unroll
;   for (int r = 0; r < 16; ++r) { p0[r] = __builtin_amdgcn_exp2f(p0[r]); p1[r] = __builtin_amdgcn_exp2f(p1[r]); }
;   float ps = 0;
; #pragma unroll
;   for (int r = 0; r < 16; ++r) ps += p0[r];
; #pragma unroll
;   for (int r = 0; r < 16; ++r) ps += p1[r];
;   { auto rr = __builtin_amdgcn_permlane32_swap(__float_as_uint(ps), __float_as_uint(ps), false, false);
;     ps = __uint_as_float(rr[0]) + __uint_as_float(rr[1]); }
;   l_reg = l_reg * alpha + ps;
; #pragma unroll
;   for (int g = 0; g < 4; ++g) {
;     int w = __builtin_amdgcn_cvt_pk_fp8_f32(p0[4 * g], p0[4 * g + 1], 0, false); p8[g] = __builtin_amdgcn_cvt_pk_fp8_f32(p0[4 * g + 2], p0[4 * g + 3], w, true);
;     int u = __builtin_amdgcn_cvt_pk_fp8_f32(p1[4 * g], p1[4 * g + 1], 0, false); p8[4 + g] = __builtin_amdgcn_cvt_pk_fp8_f32(p1[4 * g + 2], p1[4 * g + 3], u, true); }
; }
; __device__ __forceinline__ void pv8(f32x16* o, const char* Vt, const v8i32 p8, int r32, int hi) {
;   const int sw = (r32 >> 2) & 3, a0 = r32 * 64 + (((hi * 2) ^ sw) << 4), a1 = r32 * 64 + (((hi * 2 + 1) ^ sw) << 4);
; #pragma unroll
;   for (int d0 = 0; d0 < 4; ++d0) {
;     const v8i32 vf = cat8(*reinterpret_cast<const v4i32*>(Vt + d0 * 2048 + a0), *reinterpret_cast<const v4i32*>(Vt + d0 * 2048 + a1));
;     o[d0] = __builtin_amdgcn_mfma_scale_f32_32x32x64_f8f6f4(p8, vf, o[d0], 0, 0, 0, 127, 0, 127); }
; }
; __device__ __forceinline__ void qkt9(f32x16& p0, f32x16& p1, const char* Kn, const char* Kr, const v8i32* qf, const float init, int r32, int hi) {
; #pragma unroll
;   for (int r = 0; r < 16; ++r) { p0[r] = init; p1[r] = init; }
; #pragma unroll
;   for (int s = 0; s < 2; ++s) { const int c0 = s * 4 + hi * 2;
;     const v8i32 a0 = cat8(*reinterpret_cast<const v4i32*>(Kn + KN8SW(r32, c0)), *reinterpret_cast<const v4i32*>(Kn + KN8SW(r32, c0 + 1)));
;     const v8i32 a1 = cat8(*reinterpret_cast<const v4i32*>(Kn + 4096 + KN8SW(r32, c0)), *reinterpret_cast<const v4i32*>(Kn + 4096 + KN8SW(r32, c0 + 1)));
;     p0 = __builtin_amdgcn_mfma_scale_f32_32x32x64_f8f6f4(a0, qf[s], p0, 0, 0, 0, 127, 0, 124);
;     p1 = __builtin_amdgcn_mfma_scale_f32_32x32x64_f8f6f4(a1, qf[s], p1, 0, 0, 0, 127, 0, 124); }
;   { const int c0 = hi * 2;
.Lmla_s1_cont:
	ds_read_b128 v[114:117], v215 offset:16384
	ds_read_b128 v[118:121], v216 offset:16384
	ds_read_b128 v[222:225], v215 offset:20480
	ds_read_b128 v[226:229], v216 offset:20480
	v_exp_f32_e32 v0, v82
	v_exp_f32_e32 v177, v83
	v_exp_f32_e32 v179, v84
	v_exp_f32_e32 v254, v85
	v_add_f32_e32 v219, v0, v177
	v_cvt_pk_fp8_f32 v246, v0, v177
	v_add_f32_e32 v219, v179, v219
	v_add_f32_e32 v219, v254, v219
	v_cvt_pk_fp8_f32 v246, v179, v254 op_sel:[0,0,1]
	s_waitcnt lgkmcnt(2)
	v_mfma_scale_f32_32x32x64_f8f6f4 v[114:129], v[114:121], v[146:153], v[230:245], v194, v193 op_sel_hi:[0,0,0]
	v_exp_f32_e32 v0, v86
	v_exp_f32_e32 v177, v87
	v_exp_f32_e32 v179, v88
	v_exp_f32_e32 v254, v89
	v_add_f32_e32 v219, v0, v219
	v_add_f32_e32 v219, v177, v219
	v_cvt_pk_fp8_f32 v247, v0, v177
	v_add_f32_e32 v219, v179, v219
	v_add_f32_e32 v219, v254, v219
	v_cvt_pk_fp8_f32 v247, v179, v254 op_sel:[0,0,1]
	ds_read_b128 v[82:85], v213 offset:16384
	ds_read_b128 v[86:89], v214 offset:16384
	s_waitcnt lgkmcnt(2)
	v_mfma_scale_f32_32x32x64_f8f6f4 v[98:113], v[222:229], v[146:153], v[230:245], v194, v193 op_sel_hi:[0,0,0]
	ds_read_b128 v[222:225], v213 offset:20480
	ds_read_b128 v[226:229], v214 offset:20480
	v_exp_f32_e32 v0, v90
	v_exp_f32_e32 v177, v91
	v_exp_f32_e32 v179, v92
	v_exp_f32_e32 v254, v93
	v_add_f32_e32 v219, v0, v219
	v_add_f32_e32 v219, v177, v219
	v_cvt_pk_fp8_f32 v248, v0, v177
	v_add_f32_e32 v219, v179, v219
	v_add_f32_e32 v219, v254, v219
	v_cvt_pk_fp8_f32 v248, v179, v254 op_sel:[0,0,1]
	v_exp_f32_e32 v0, v94
	v_exp_f32_e32 v177, v95
	v_exp_f32_e32 v179, v96
	v_exp_f32_e32 v254, v97
	v_add_f32_e32 v219, v0, v219
	v_add_f32_e32 v219, v177, v219
	v_cvt_pk_fp8_f32 v249, v0, v177
	v_add_f32_e32 v219, v179, v219
	v_add_f32_e32 v219, v254, v219
	v_cvt_pk_fp8_f32 v249, v179, v254 op_sel:[0,0,1]
	ds_read_b128 v[90:93], v185 offset:32768
	ds_read_b128 v[94:97], v186 offset:32768
	s_waitcnt lgkmcnt(4)
	v_mfma_scale_f32_32x32x64_f8f6f4 v[114:129], v[82:89], v[138:145], v[114:129], v194, v193 op_sel_hi:[0,0,0]
	v_exp_f32_e32 v0, v66
	v_exp_f32_e32 v177, v67
	v_exp_f32_e32 v179, v68
	v_exp_f32_e32 v254, v69
	v_add_f32_e32 v219, v0, v219
	v_add_f32_e32 v219, v177, v219
	v_cvt_pk_fp8_f32 v250, v0, v177
	v_add_f32_e32 v219, v179, v219
	v_add_f32_e32 v219, v254, v219
	v_cvt_pk_fp8_f32 v250, v179, v254 op_sel:[0,0,1]
	s_waitcnt lgkmcnt(2)
	v_mfma_scale_f32_32x32x64_f8f6f4 v[98:113], v[222:229], v[138:145], v[98:113], v194, v193 op_sel_hi:[0,0,0]
	ds_read_b128 v[222:225], v185 offset:34816
	ds_read_b128 v[226:229], v186 offset:34816
	v_exp_f32_e32 v0, v70
	v_exp_f32_e32 v177, v71
	v_exp_f32_e32 v179, v72
	v_exp_f32_e32 v254, v73
	v_add_f32_e32 v219, v0, v219
	v_add_f32_e32 v219, v177, v219
	v_cvt_pk_fp8_f32 v251, v0, v177
	v_add_f32_e32 v219, v179, v219
	v_add_f32_e32 v219, v254, v219
	v_cvt_pk_fp8_f32 v251, v179, v254 op_sel:[0,0,1]
	v_exp_f32_e32 v0, v74
	v_exp_f32_e32 v177, v75
	v_exp_f32_e32 v179, v76
	v_exp_f32_e32 v254, v77
	v_add_f32_e32 v219, v0, v219
	v_add_f32_e32 v219, v177, v219
	v_cvt_pk_fp8_f32 v252, v0, v177
	v_add_f32_e32 v219, v179, v219
	v_add_f32_e32 v219, v254, v219
	v_cvt_pk_fp8_f32 v252, v179, v254 op_sel:[0,0,1]
	s_waitcnt lgkmcnt(2)
	v_mfma_scale_f32_32x32x64_f8f6f4 v[114:129], v[90:97], v[130:137], v[114:129], v194, v193 op_sel_hi:[0,0,0]
	v_exp_f32_e32 v0, v78
	v_exp_f32_e32 v177, v79
	v_exp_f32_e32 v179, v80
	v_exp_f32_e32 v254, v81
	v_add_f32_e32 v219, v0, v219
	v_add_f32_e32 v219, v177, v219
	v_cvt_pk_fp8_f32 v253, v0, v177
	v_add_f32_e32 v219, v179, v219
	v_add_f32_e32 v219, v254, v219
	v_cvt_pk_fp8_f32 v253, v179, v254 op_sel:[0,0,1]
	ds_read_b128 v[90:93], v185 offset:43008
	ds_read_b128 v[94:97], v186 offset:43008
	ds_read_b128 v[82:85], v185 offset:45056
	ds_read_b128 v[86:89], v186 offset:45056
	ds_read_b128 v[74:77], v185 offset:47104
	ds_read_b128 v[78:81], v186 offset:47104
	ds_read_b128 v[66:69], v185 offset:49152
	ds_read_b128 v[70:73], v186 offset:49152
	s_waitcnt lgkmcnt(8)
	v_mfma_scale_f32_32x32x64_f8f6f4 v[98:113], v[222:229], v[130:137], v[98:113], v194, v193 op_sel_hi:[0,0,0]
	v_mov_b32_e32 v0, v219
	s_nop 1
	v_permlane32_swap_b32_e32 v219, v0
	v_add_f32_e32 v219, v219, v0
	v_fma_f32 v209, v209, v218, v219
	v_max_f32_e32 v177, v114, v115
	v_max3_f32 v177, v177, v116, v117
	v_max3_f32 v177, v177, v118, v119
	v_max3_f32 v177, v177, v120, v121
	v_max3_f32 v177, v177, v122, v123
	v_max3_f32 v177, v177, v124, v125
	v_max3_f32 v177, v177, v126, v127
	v_max3_f32 v177, v177, v128, v129
	s_waitcnt lgkmcnt(6)
	v_mfma_scale_f32_32x32x64_f8f6f4 v[50:65], v[246:253], v[90:97], v[50:65], v194, v194 op_sel_hi:[0,0,0]
	s_waitcnt lgkmcnt(4)
	v_mfma_scale_f32_32x32x64_f8f6f4 v[34:49], v[246:253], v[82:89], v[34:49], v194, v194 op_sel_hi:[0,0,0]
	s_waitcnt vmcnt(0)
	s_waitcnt lgkmcnt(0)
	s_barrier
	v_max_f32_e32 v0, v98, v99
	v_max3_f32 v0, v0, v100, v101
	v_max3_f32 v0, v0, v102, v103
	v_max3_f32 v0, v0, v104, v105
	s_waitcnt lgkmcnt(2)
	v_mfma_scale_f32_32x32x64_f8f6f4 v[18:33], v[246:253], v[74:81], v[18:33], v194, v194 op_sel_hi:[0,0,0]
	s_add_i32 m0, s98, 0xa800
	s_nop 0
	global_load_lds_dwordx4 v176, s[18:19]
	s_add_i32 m0, s98, 0xc800
	s_nop 0
	global_load_lds_dwordx4 v178, s[16:17]
	v_add_u32_e32 v176, 0x2000, v176
	v_add_u32_e32 v178, 0x20000, v178
	v_max3_f32 v0, v0, v106, v107
	v_max3_f32 v0, v0, v108, v109
	v_max3_f32 v0, v0, v110, v111
	v_max3_f32 v0, v0, v112, v113
	s_waitcnt lgkmcnt(0)
	v_mfma_scale_f32_32x32x64_f8f6f4 v[2:17], v[246:253], v[66:73], v[2:17], v194, v194 op_sel_hi:[0,0,0]
	v_max_f32_e32 v177, v177, v0
	v_mov_b32_e32 v0, v177
	v_mov_b32_e32 v221, 1.0
	s_nop 0
	v_permlane32_swap_b32_e32 v177, v0
	v_max_f32_e32 v177, v177, v0
	v_cmp_ge_f32_e32 vcc, s90, v177
	s_cmp_eq_u64 vcc, exec
	s_cbranch_scc0 .Lmla_s2_newmax
; __device__ __forceinline__ void finishSM9(f32x16& p0, f32x16& p1, float alpha, float& l_reg, v8i32& p8) {
; #pragma unroll
;   for (int r = 0; r < 16; ++r) { p0[r] = __builtin_amdgcn_exp2f(p0[r]); p1[r] = __builtin_amdgcn_exp2f(p1[r]); }
;   float ps = 0;
; #pragma unroll
;   for (int r = 0; r < 16; ++r) ps += p0[r];
; #pragma unroll
;   for (int r = 0; r < 16; ++r) ps += p1[r];
;   { auto rr = __builtin_amdgcn_permlane32_swap(__float_as_uint(ps), __float_as_uint(ps), false, false);
;     ps = __uint_as_float(rr[0]) + __uint_as_float(rr[1]); }
;   l_reg = l_reg * alpha + ps;
; #pragma unroll
;   for (int g = 0; g < 4; ++g) {
;     int w = __builtin_amdgcn_cvt_pk_fp8_f32(p0[4 * g], p0[4 * g + 1], 0, false); p8[g] = __builtin_amdgcn_cvt_pk_fp8_f32(p0[4 * g + 2], p0[4 * g + 3], w, true);
;     int u = __builtin_amdgcn_cvt_pk_fp8_f32(p1[4 * g], p1[4 * g + 1], 0, false); p8[4 + g] = __builtin_amdgcn_cvt_pk_fp8_f32(p1[4 * g + 2], p1[4 * g + 3], u, true); }
; }
; __device__ __forceinline__ void pv8(f32x16* o, const char* Vt, const v8i32 p8, int r32, int hi) {
;   const int sw = (r32 >> 2) & 3, a0 = r32 * 64 + (((hi * 2) ^ sw) << 4), a1 = r32 * 64 + (((hi * 2 + 1) ^ sw) << 4);
; #pragma unroll
;   for (int d0 = 0; d0 < 4; ++d0) {
;     const v8i32 vf = cat8(*reinterpret_cast<const v4i32*>(Vt + d0 * 2048 + a0), *reinterpret_cast<const v4i32*>(Vt + d0 * 2048 + a1));
;     o[d0] = __builtin_amdgcn_mfma_scale_f32_32x32x64_f8f6f4(p8, vf, o[d0], 0, 0, 0, 127, 0, 127); }
; }
; __device__ __forceinline__ void qkt9(f32x16& p0, f32x16& p1, const char* Kn, const char* Kr, const v8i32* qf, const float init, int r32, int hi) {
; #pragma unroll
;   for (int r = 0; r < 16; ++r) { p0[r] = init; p1[r] = init; }
; #pragma unroll
;   for (int s = 0; s < 2; ++s) { const int c0 = s * 4 + hi * 2;
;     const v8i32 a0 = cat8(*reinterpret_cast<const v4i32*>(Kn + KN8SW(r32, c0)), *reinterpret_cast<const v4i32*>(Kn + KN8SW(r32, c0 + 1)));
;     const v8i32 a1 = cat8(*reinterpret_cast<const v4i32*>(Kn + 4096 + KN8SW(r32, c0)), *reinterpret_cast<const v4i32*>(Kn + 4096 + KN8SW(r32, c0 + 1)));
;     p0 = __builtin_amdgcn_mfma_scale_f32_32x32x64_f8f6f4(a0, qf[s], p0, 0, 0, 0, 127, 0, 124);
;     p1 = __builtin_amdgcn_mfma_scale_f32_32x32x64_f8f6f4(a1, qf[s], p1, 0, 0, 0, 127, 0, 124); }
;   { const int c0 = hi * 2;
.Lmla_s2_cont:
	ds_read_b128 v[82:85], v215 offset:24576
	ds_read_b128 v[86:89], v216 offset:24576
	ds_read_b128 v[222:225], v215 offset:28672
	ds_read_b128 v[226:229], v216 offset:28672
	v_exp_f32_e32 v0, v114
	v_exp_f32_e32 v177, v115
	v_exp_f32_e32 v179, v116
	v_exp_f32_e32 v254, v117
	v_add_f32_e32 v219, v0, v177
	v_cvt_pk_fp8_f32 v246, v0, v177
	v_add_f32_e32 v219, v179, v219
	v_add_f32_e32 v219, v254, v219
	v_cvt_pk_fp8_f32 v246, v179, v254 op_sel:[0,0,1]
	s_waitcnt lgkmcnt(2)
	v_mfma_scale_f32_32x32x64_f8f6f4 v[82:97], v[82:89], v[146:153], v[230:245], v194, v193 op_sel_hi:[0,0,0]
	v_exp_f32_e32 v0, v118
	v_exp_f32_e32 v177, v119
	v_exp_f32_e32 v179, v120
	v_exp_f32_e32 v254, v121
	v_add_f32_e32 v219, v0, v219
	v_add_f32_e32 v219, v177, v219
	v_cvt_pk_fp8_f32 v247, v0, v177
	v_add_f32_e32 v219, v179, v219
	v_add_f32_e32 v219, v254, v219
	v_cvt_pk_fp8_f32 v247, v179, v254 op_sel:[0,0,1]
	ds_read_b128 v[114:117], v213 offset:24576
	ds_read_b128 v[118:121], v214 offset:24576
	s_waitcnt lgkmcnt(2)
	v_mfma_scale_f32_32x32x64_f8f6f4 v[66:81], v[222:229], v[146:153], v[230:245], v194, v193 op_sel_hi:[0,0,0]
	ds_read_b128 v[222:225], v213 offset:28672
	ds_read_b128 v[226:229], v214 offset:28672
	v_exp_f32_e32 v0, v122
	v_exp_f32_e32 v177, v123
	v_exp_f32_e32 v179, v124
	v_exp_f32_e32 v254, v125
	v_add_f32_e32 v219, v0, v219
	v_add_f32_e32 v219, v177, v219
	v_cvt_pk_fp8_f32 v248, v0, v177
	v_add_f32_e32 v219, v179, v219
	v_add_f32_e32 v219, v254, v219
	v_cvt_pk_fp8_f32 v248, v179, v254 op_sel:[0,0,1]
	v_exp_f32_e32 v0, v126
	v_exp_f32_e32 v177, v127
	v_exp_f32_e32 v179, v128
	v_exp_f32_e32 v254, v129
	v_add_f32_e32 v219, v0, v219
	v_add_f32_e32 v219, v177, v219
	v_cvt_pk_fp8_f32 v249, v0, v177
	v_add_f32_e32 v219, v179, v219
	v_add_f32_e32 v219, v254, v219
	v_cvt_pk_fp8_f32 v249, v179, v254 op_sel:[0,0,1]
	ds_read_b128 v[122:125], v185 offset:36864
	ds_read_b128 v[126:129], v186 offset:36864
	s_waitcnt lgkmcnt(4)
	v_mfma_scale_f32_32x32x64_f8f6f4 v[82:97], v[114:121], v[138:145], v[82:97], v194, v193 op_sel_hi:[0,0,0]
	v_exp_f32_e32 v0, v98
	v_exp_f32_e32 v177, v99
	v_exp_f32_e32 v179, v100
	v_exp_f32_e32 v254, v101
	v_add_f32_e32 v219, v0, v219
	v_add_f32_e32 v219, v177, v219
	v_cvt_pk_fp8_f32 v250, v0, v177
	v_add_f32_e32 v219, v179, v219
	v_add_f32_e32 v219, v254, v219
	v_cvt_pk_fp8_f32 v250, v179, v254 op_sel:[0,0,1]
	s_waitcnt lgkmcnt(2)
	v_mfma_scale_f32_32x32x64_f8f6f4 v[66:81], v[222:229], v[138:145], v[66:81], v194, v193 op_sel_hi:[0,0,0]
	ds_read_b128 v[222:225], v185 offset:38912
	ds_read_b128 v[226:229], v186 offset:38912
	v_exp_f32_e32 v0, v102
	v_exp_f32_e32 v177, v103
	v_exp_f32_e32 v179, v104
	v_exp_f32_e32 v254, v105
	v_add_f32_e32 v219, v0, v219
	v_add_f32_e32 v219, v177, v219
	v_cvt_pk_fp8_f32 v251, v0, v177
	v_add_f32_e32 v219, v179, v219
	v_add_f32_e32 v219, v254, v219
	v_cvt_pk_fp8_f32 v251, v179, v254 op_sel:[0,0,1]
	v_exp_f32_e32 v0, v106
	v_exp_f32_e32 v177, v107
	v_exp_f32_e32 v179, v108
	v_exp_f32_e32 v254, v109
	v_add_f32_e32 v219, v0, v219
	v_add_f32_e32 v219, v177, v219
	v_cvt_pk_fp8_f32 v252, v0, v177
	v_add_f32_e32 v219, v179, v219
	v_add_f32_e32 v219, v254, v219
	v_cvt_pk_fp8_f32 v252, v179, v254 op_sel:[0,0,1]
	s_waitcnt lgkmcnt(2)
	v_mfma_scale_f32_32x32x64_f8f6f4 v[82:97], v[122:129], v[130:137], v[82:97], v194, v193 op_sel_hi:[0,0,0]
	v_exp_f32_e32 v0, v110
	v_exp_f32_e32 v177, v111
	v_exp_f32_e32 v179, v112
	v_exp_f32_e32 v254, v113
	v_add_f32_e32 v219, v0, v219
	v_add_f32_e32 v219, v177, v219
	v_cvt_pk_fp8_f32 v253, v0, v177
	v_add_f32_e32 v219, v179, v219
	v_add_f32_e32 v219, v254, v219
	v_cvt_pk_fp8_f32 v253, v179, v254 op_sel:[0,0,1]
	ds_read_b128 v[122:125], v185 offset:0
	ds_read_b128 v[126:129], v186 offset:0
	ds_read_b128 v[114:117], v185 offset:2048
	ds_read_b128 v[118:121], v186 offset:2048
	ds_read_b128 v[106:109], v185 offset:4096
	ds_read_b128 v[110:113], v186 offset:4096
	ds_read_b128 v[98:101], v185 offset:6144
	ds_read_b128 v[102:105], v186 offset:6144
	s_waitcnt lgkmcnt(8)
	v_mfma_scale_f32_32x32x64_f8f6f4 v[66:81], v[222:229], v[130:137], v[66:81], v194, v193 op_sel_hi:[0,0,0]
	v_mov_b32_e32 v0, v219
	s_nop 1
	v_permlane32_swap_b32_e32 v219, v0
	v_add_f32_e32 v219, v219, v0
	v_fma_f32 v209, v209, v221, v219
	v_max_f32_e32 v177, v82, v83
	v_max3_f32 v177, v177, v84, v85
	v_max3_f32 v177, v177, v86, v87
	v_max3_f32 v177, v177, v88, v89
	v_max3_f32 v177, v177, v90, v91
	v_max3_f32 v177, v177, v92, v93
	v_max3_f32 v177, v177, v94, v95
	v_max3_f32 v177, v177, v96, v97
	s_waitcnt lgkmcnt(6)
	v_mfma_scale_f32_32x32x64_f8f6f4 v[50:65], v[246:253], v[122:129], v[50:65], v194, v194 op_sel_hi:[0,0,0]
	s_waitcnt lgkmcnt(4)
	v_mfma_scale_f32_32x32x64_f8f6f4 v[34:49], v[246:253], v[114:121], v[34:49], v194, v194 op_sel_hi:[0,0,0]
	s_waitcnt vmcnt(0)
	s_waitcnt lgkmcnt(0)
	s_barrier
	v_max_f32_e32 v0, v66, v67
	v_max3_f32 v0, v0, v68, v69
	v_max3_f32 v0, v0, v70, v71
	v_max3_f32 v0, v0, v72, v73
	s_waitcnt lgkmcnt(2)
	v_mfma_scale_f32_32x32x64_f8f6f4 v[18:33], v[246:253], v[106:113], v[18:33], v194, v194 op_sel_hi:[0,0,0]
	s_add_i32 m0, s98, 0x0
	s_nop 0
	global_load_lds_dwordx4 v176, s[18:19]
	s_add_i32 m0, s98, 0x4000
	s_nop 0
	global_load_lds_dwordx4 v178, s[16:17]
	v_add_u32_e32 v176, 0x2000, v176
	v_add_u32_e32 v178, 0x20000, v178
	v_max3_f32 v0, v0, v74, v75
	v_max3_f32 v0, v0, v76, v77
	v_max3_f32 v0, v0, v78, v79
	v_max3_f32 v0, v0, v80, v81
	s_waitcnt lgkmcnt(0)
	v_mfma_scale_f32_32x32x64_f8f6f4 v[2:17], v[246:253], v[98:105], v[2:17], v194, v194 op_sel_hi:[0,0,0]
	v_max_f32_e32 v177, v177, v0
	v_mov_b32_e32 v0, v177
	v_mov_b32_e32 v218, 1.0
	s_nop 0
	v_permlane32_swap_b32_e32 v177, v0
	v_max_f32_e32 v177, v177, v0
	v_cmp_ge_f32_e32 vcc, s90, v177
	s_cmp_eq_u64 vcc, exec
	s_cbranch_scc0 .Lmla_s3_newmax
; __device__ __forceinline__ void finishSM9(f32x16& p0, f32x16& p1, float alpha, float& l_reg, v8i32& p8) {
; #pragma unroll
;   for (int r = 0; r < 16; ++r) { p0[r] = __builtin_amdgcn_exp2f(p0[r]); p1[r] = __builtin_amdgcn_exp2f(p1[r]); }
;   float ps = 0;
; #pragma unroll
;   for (int r = 0; r < 16; ++r) ps += p0[r];
; #pragma unroll
;   for (int r = 0; r < 16; ++r) ps += p1[r];
;   { auto rr = __builtin_amdgcn_permlane32_swap(__float_as_uint(ps), __float_as_uint(ps), false, false);
;     ps = __uint_as_float(rr[0]) + __uint_as_float(rr[1]); }
;   l_reg = l_reg * alpha + ps;
; #pragma unroll
;   for (int g = 0; g < 4; ++g) {
;     int w = __builtin_amdgcn_cvt_pk_fp8_f32(p0[4 * g], p0[4 * g + 1], 0, false); p8[g] = __builtin_amdgcn_cvt_pk_fp8_f32(p0[4 * g + 2], p0[4 * g + 3], w, true);
;     int u = __builtin_amdgcn_cvt_pk_fp8_f32(p1[4 * g], p1[4 * g + 1], 0, false); p8[4 + g] = __builtin_amdgcn_cvt_pk_fp8_f32(p1[4 * g + 2], p1[4 * g + 3], u, true); }
; }
; __device__ __forceinline__ void pv8(f32x16* o, const char* Vt, const v8i32 p8, int r32, int hi) {
;   const int sw = (r32 >> 2) & 3, a0 = r32 * 64 + (((hi * 2) ^ sw) << 4), a1 = r32 * 64 + (((hi * 2 + 1) ^ sw) << 4);
; #pragma unroll
;   for (int d0 = 0; d0 < 4; ++d0) {
;     const v8i32 vf = cat8(*reinterpret_cast<const v4i32*>(Vt + d0 * 2048 + a0), *reinterpret_cast<const v4i32*>(Vt + d0 * 2048 + a1));
;     o[d0] = __builtin_amdgcn_mfma_scale_f32_32x32x64_f8f6f4(p8, vf, o[d0], 0, 0, 0, 127, 0, 127); }
; }
; __device__ __forceinline__ void qkt9(f32x16& p0, f32x16& p1, const char* Kn, const char* Kr, const v8i32* qf, const float init, int r32, int hi) {
; #pragma unroll
;   for (int r = 0; r < 16; ++r) { p0[r] = init; p1[r] = init; }
; #pragma unroll
;   for (int s = 0; s < 2; ++s) { const int c0 = s * 4 + hi * 2;
;     const v8i32 a0 = cat8(*reinterpret_cast<const v4i32*>(Kn + KN8SW(r32, c0)), *reinterpret_cast<const v4i32*>(Kn + KN8SW(r32, c0 + 1)));
;     const v8i32 a1 = cat8(*reinterpret_cast<const v4i32*>(Kn + 4096 + KN8SW(r32, c0)), *reinterpret_cast<const v4i32*>(Kn + 4096 + KN8SW(r32, c0 + 1)));
;     p0 = __builtin_amdgcn_mfma_scale_f32_32x32x64_f8f6f4(a0, qf[s], p0, 0, 0, 0, 127, 0, 124);
;     p1 = __builtin_amdgcn_mfma_scale_f32_32x32x64_f8f6f4(a1, qf[s], p1, 0, 0, 0, 127, 0, 124); }
;   { const int c0 = hi * 2;
.Lmla_s3_cont:
	ds_read_b128 v[114:117], v215 offset:51200
	ds_read_b128 v[118:121], v216 offset:51200
	ds_read_b128 v[222:225], v215 offset:55296
	ds_read_b128 v[226:229], v216 offset:55296
	v_exp_f32_e32 v0, v82
	v_exp_f32_e32 v177, v83
	v_exp_f32_e32 v179, v84
	v_exp_f32_e32 v254, v85
	v_add_f32_e32 v219, v0, v177
	v_cvt_pk_fp8_f32 v246, v0, v177
	v_add_f32_e32 v219, v179, v219
	v_add_f32_e32 v219, v254, v219
	v_cvt_pk_fp8_f32 v246, v179, v254 op_sel:[0,0,1]
	s_waitcnt lgkmcnt(2)
	v_mfma_scale_f32_32x32x64_f8f6f4 v[114:129], v[114:121], v[146:153], v[230:245], v194, v193 op_sel_hi:[0,0,0]
	v_exp_f32_e32 v0, v86
	v_exp_f32_e32 v177, v87
	v_exp_f32_e32 v179, v88
	v_exp_f32_e32 v254, v89
	v_add_f32_e32 v219, v0, v219
	v_add_f32_e32 v219, v177, v219
	v_cvt_pk_fp8_f32 v247, v0, v177
	v_add_f32_e32 v219, v179, v219
	v_add_f32_e32 v219, v254, v219
	v_cvt_pk_fp8_f32 v247, v179, v254 op_sel:[0,0,1]
	ds_read_b128 v[82:85], v213 offset:51200
	ds_read_b128 v[86:89], v214 offset:51200
	s_waitcnt lgkmcnt(2)
	v_mfma_scale_f32_32x32x64_f8f6f4 v[98:113], v[222:229], v[146:153], v[230:245], v194, v193 op_sel_hi:[0,0,0]
	ds_read_b128 v[222:225], v213 offset:55296
	ds_read_b128 v[226:229], v214 offset:55296
	v_exp_f32_e32 v0, v90
	v_exp_f32_e32 v177, v91
	v_exp_f32_e32 v179, v92
	v_exp_f32_e32 v254, v93
	v_add_f32_e32 v219, v0, v219
	v_add_f32_e32 v219, v177, v219
	v_cvt_pk_fp8_f32 v248, v0, v177
	v_add_f32_e32 v219, v179, v219
	v_add_f32_e32 v219, v254, v219
	v_cvt_pk_fp8_f32 v248, v179, v254 op_sel:[0,0,1]
	v_exp_f32_e32 v0, v94
	v_exp_f32_e32 v177, v95
	v_exp_f32_e32 v179, v96
	v_exp_f32_e32 v254, v97
	v_add_f32_e32 v219, v0, v219
	v_add_f32_e32 v219, v177, v219
	v_cvt_pk_fp8_f32 v249, v0, v177
	v_add_f32_e32 v219, v179, v219
	v_add_f32_e32 v219, v254, v219
	v_cvt_pk_fp8_f32 v249, v179, v254 op_sel:[0,0,1]
	ds_read_b128 v[90:93], v185 offset:59392
	ds_read_b128 v[94:97], v186 offset:59392
	s_waitcnt lgkmcnt(4)
	v_mfma_scale_f32_32x32x64_f8f6f4 v[114:129], v[82:89], v[138:145], v[114:129], v194, v193 op_sel_hi:[0,0,0]
	v_exp_f32_e32 v0, v66
	v_exp_f32_e32 v177, v67
	v_exp_f32_e32 v179, v68
	v_exp_f32_e32 v254, v69
	v_add_f32_e32 v219, v0, v219
	v_add_f32_e32 v219, v177, v219
	v_cvt_pk_fp8_f32 v250, v0, v177
	v_add_f32_e32 v219, v179, v219
	v_add_f32_e32 v219, v254, v219
	v_cvt_pk_fp8_f32 v250, v179, v254 op_sel:[0,0,1]
	s_waitcnt lgkmcnt(2)
	v_mfma_scale_f32_32x32x64_f8f6f4 v[98:113], v[222:229], v[138:145], v[98:113], v194, v193 op_sel_hi:[0,0,0]
	ds_read_b128 v[222:225], v185 offset:61440
	ds_read_b128 v[226:229], v186 offset:61440
	v_exp_f32_e32 v0, v70
	v_exp_f32_e32 v177, v71
	v_exp_f32_e32 v179, v72
	v_exp_f32_e32 v254, v73
	v_add_f32_e32 v219, v0, v219
	v_add_f32_e32 v219, v177, v219
	v_cvt_pk_fp8_f32 v251, v0, v177
	v_add_f32_e32 v219, v179, v219
	v_add_f32_e32 v219, v254, v219
	v_cvt_pk_fp8_f32 v251, v179, v254 op_sel:[0,0,1]
	v_exp_f32_e32 v0, v74
	v_exp_f32_e32 v177, v75
	v_exp_f32_e32 v179, v76
	v_exp_f32_e32 v254, v77
	v_add_f32_e32 v219, v0, v219
	v_add_f32_e32 v219, v177, v219
	v_cvt_pk_fp8_f32 v252, v0, v177
	v_add_f32_e32 v219, v179, v219
	v_add_f32_e32 v219, v254, v219
	v_cvt_pk_fp8_f32 v252, v179, v254 op_sel:[0,0,1]
	s_waitcnt lgkmcnt(2)
	v_mfma_scale_f32_32x32x64_f8f6f4 v[114:129], v[90:97], v[130:137], v[114:129], v194, v193 op_sel_hi:[0,0,0]
	v_exp_f32_e32 v0, v78
	v_exp_f32_e32 v177, v79
	v_exp_f32_e32 v179, v80
	v_exp_f32_e32 v254, v81
	v_add_f32_e32 v219, v0, v219
	v_add_f32_e32 v219, v177, v219
	v_cvt_pk_fp8_f32 v253, v0, v177
	v_add_f32_e32 v219, v179, v219
	v_add_f32_e32 v219, v254, v219
	v_cvt_pk_fp8_f32 v253, v179, v254 op_sel:[0,0,1]
	ds_read_b128 v[90:93], v185 offset:8192
	ds_read_b128 v[94:97], v186 offset:8192
	ds_read_b128 v[82:85], v185 offset:10240
	ds_read_b128 v[86:89], v186 offset:10240
	ds_read_b128 v[74:77], v185 offset:12288
	ds_read_b128 v[78:81], v186 offset:12288
	ds_read_b128 v[66:69], v185 offset:14336
	ds_read_b128 v[70:73], v186 offset:14336
	s_waitcnt lgkmcnt(8)
	v_mfma_scale_f32_32x32x64_f8f6f4 v[98:113], v[222:229], v[130:137], v[98:113], v194, v193 op_sel_hi:[0,0,0]
	v_mov_b32_e32 v0, v219
	s_nop 1
	v_permlane32_swap_b32_e32 v219, v0
	v_add_f32_e32 v219, v219, v0
	v_fma_f32 v209, v209, v218, v219
	v_max_f32_e32 v177, v114, v115
	v_max3_f32 v177, v177, v116, v117
	v_max3_f32 v177, v177, v118, v119
	v_max3_f32 v177, v177, v120, v121
	v_max3_f32 v177, v177, v122, v123
	v_max3_f32 v177, v177, v124, v125
	v_max3_f32 v177, v177, v126, v127
	v_max3_f32 v177, v177, v128, v129
	s_waitcnt lgkmcnt(6)
	v_mfma_scale_f32_32x32x64_f8f6f4 v[50:65], v[246:253], v[90:97], v[50:65], v194, v194 op_sel_hi:[0,0,0]
	s_waitcnt lgkmcnt(4)
	v_mfma_scale_f32_32x32x64_f8f6f4 v[34:49], v[246:253], v[82:89], v[34:49], v194, v194 op_sel_hi:[0,0,0]
	s_waitcnt vmcnt(0)
	s_waitcnt lgkmcnt(0)
	s_barrier
	v_max_f32_e32 v0, v98, v99
	v_max3_f32 v0, v0, v100, v101
	v_max3_f32 v0, v0, v102, v103
	v_max3_f32 v0, v0, v104, v105
	s_waitcnt lgkmcnt(2)
	v_mfma_scale_f32_32x32x64_f8f6f4 v[18:33], v[246:253], v[74:81], v[18:33], v194, v194 op_sel_hi:[0,0,0]
	s_add_i32 m0, s98, 0x2000
	s_nop 0
	global_load_lds_dwordx4 v176, s[18:19]
	s_add_i32 m0, s98, 0x6000
	s_nop 0
	global_load_lds_dwordx4 v178, s[16:17]
	v_add_u32_e32 v176, 0x2000, v176
	v_add_u32_e32 v178, 0x20000, v178
	v_max3_f32 v0, v0, v106, v107
	v_max3_f32 v0, v0, v108, v109
	v_max3_f32 v0, v0, v110, v111
	v_max3_f32 v0, v0, v112, v113
	s_waitcnt lgkmcnt(0)
	v_mfma_scale_f32_32x32x64_f8f6f4 v[2:17], v[246:253], v[66:73], v[2:17], v194, v194 op_sel_hi:[0,0,0]
	v_max_f32_e32 v177, v177, v0
	v_mov_b32_e32 v0, v177
	v_mov_b32_e32 v221, 1.0
	s_nop 0
	v_permlane32_swap_b32_e32 v177, v0
	v_max_f32_e32 v177, v177, v0
	v_cmp_ge_f32_e32 vcc, s90, v177
	s_cmp_eq_u64 vcc, exec
	s_cbranch_scc0 .Lmla_s4_newmax
; __device__ __forceinline__ void finishSM9(f32x16& p0, f32x16& p1, float alpha, float& l_reg, v8i32& p8) {
; #pragma unroll
;   for (int r = 0; r < 16; ++r) { p0[r] = __builtin_amdgcn_exp2f(p0[r]); p1[r] = __builtin_amdgcn_exp2f(p1[r]); }
;   float ps = 0;
; #pragma unroll
;   for (int r = 0; r < 16; ++r) ps += p0[r];
; #pragma unroll
;   for (int r = 0; r < 16; ++r) ps += p1[r];
;   { auto rr = __builtin_amdgcn_permlane32_swap(__float_as_uint(ps), __float_as_uint(ps), false, false);
;     ps = __uint_as_float(rr[0]) + __uint_as_float(rr[1]); }
;   l_reg = l_reg * alpha + ps;
; #pragma unroll
;   for (int g = 0; g < 4; ++g) {
;     int w = __builtin_amdgcn_cvt_pk_fp8_f32(p0[4 * g], p0[4 * g + 1], 0, false); p8[g] = __builtin_amdgcn_cvt_pk_fp8_f32(p0[4 * g + 2], p0[4 * g + 3], w, true);
;     int u = __builtin_amdgcn_cvt_pk_fp8_f32(p1[4 * g], p1[4 * g + 1], 0, false); p8[4 + g] = __builtin_amdgcn_cvt_pk_fp8_f32(p1[4 * g + 2], p1[4 * g + 3], u, true); }
; }
; __device__ __forceinline__ void pv8(f32x16* o, const char* Vt, const v8i32 p8, int r32, int hi) {
;   const int sw = (r32 >> 2) & 3, a0 = r32 * 64 + (((hi * 2) ^ sw) << 4), a1 = r32 * 64 + (((hi * 2 + 1) ^ sw) << 4);
; #pragma unroll
;   for (int d0 = 0; d0 < 4; ++d0) {
;     const v8i32 vf = cat8(*reinterpret_cast<const v4i32*>(Vt + d0 * 2048 + a0), *reinterpret_cast<const v4i32*>(Vt + d0 * 2048 + a1));
;     o[d0] = __builtin_amdgcn_mfma_scale_f32_32x32x64_f8f6f4(p8, vf, o[d0], 0, 0, 0, 127, 0, 127); }
; }
; __device__ __forceinline__ void qkt9(f32x16& p0, f32x16& p1, const char* Kn, const char* Kr, const v8i32* qf, const float init, int r32, int hi) {
; #pragma unroll
;   for (int r = 0; r < 16; ++r) { p0[r] = init; p1[r] = init; }
; #pragma unroll
;   for (int s = 0; s < 2; ++s) { const int c0 = s * 4 + hi * 2;
;     const v8i32 a0 = cat8(*reinterpret_cast<const v4i32*>(Kn + KN8SW(r32, c0)), *reinterpret_cast<const v4i32*>(Kn + KN8SW(r32, c0 + 1)));
;     const v8i32 a1 = cat8(*reinterpret_cast<const v4i32*>(Kn + 4096 + KN8SW(r32, c0)), *reinterpret_cast<const v4i32*>(Kn + 4096 + KN8SW(r32, c0 + 1)));
;     p0 = __builtin_amdgcn_mfma_scale_f32_32x32x64_f8f6f4(a0, qf[s], p0, 0, 0, 0, 127, 0, 124);
;     p1 = __builtin_amdgcn_mfma_scale_f32_32x32x64_f8f6f4(a1, qf[s], p1, 0, 0, 0, 127, 0, 124); }
;   { const int c0 = hi * 2;
.Lmla_s4_cont:
	ds_read_b128 v[82:85], v215 offset:16384
	ds_read_b128 v[86:89], v216 offset:16384
	ds_read_b128 v[222:225], v215 offset:20480
	ds_read_b128 v[226:229], v216 offset:20480
	v_exp_f32_e32 v0, v114
	v_exp_f32_e32 v177, v115
	v_exp_f32_e32 v179, v116
	v_exp_f32_e32 v254, v117
	v_add_f32_e32 v219, v0, v177
	v_cvt_pk_fp8_f32 v246, v0, v177
	v_add_f32_e32 v219, v179, v219
	v_add_f32_e32 v219, v254, v219
	v_cvt_pk_fp8_f32 v246, v179, v254 op_sel:[0,0,1]
	s_waitcnt lgkmcnt(2)
	v_mfma_scale_f32_32x32x64_f8f6f4 v[82:97], v[82:89], v[146:153], v[230:245], v194, v193 op_sel_hi:[0,0,0]
	v_exp_f32_e32 v0, v118
	v_exp_f32_e32 v177, v119
	v_exp_f32_e32 v179, v120
	v_exp_f32_e32 v254, v121
	v_add_f32_e32 v219, v0, v219
	v_add_f32_e32 v219, v177, v219
	v_cvt_pk_fp8_f32 v247, v0, v177
	v_add_f32_e32 v219, v179, v219
	v_add_f32_e32 v219, v254, v219
	v_cvt_pk_fp8_f32 v247, v179, v254 op_sel:[0,0,1]
	ds_read_b128 v[114:117], v213 offset:16384
	ds_read_b128 v[118:121], v214 offset:16384
	s_waitcnt lgkmcnt(2)
	v_mfma_scale_f32_32x32x64_f8f6f4 v[66:81], v[222:229], v[146:153], v[230:245], v194, v193 op_sel_hi:[0,0,0]
	ds_read_b128 v[222:225], v213 offset:20480
	ds_read_b128 v[226:229], v214 offset:20480
	v_exp_f32_e32 v0, v122
	v_exp_f32_e32 v177, v123
	v_exp_f32_e32 v179, v124
	v_exp_f32_e32 v254, v125
	v_add_f32_e32 v219, v0, v219
	v_add_f32_e32 v219, v177, v219
	v_cvt_pk_fp8_f32 v248, v0, v177
	v_add_f32_e32 v219, v179, v219
	v_add_f32_e32 v219, v254, v219
	v_cvt_pk_fp8_f32 v248, v179, v254 op_sel:[0,0,1]
	v_exp_f32_e32 v0, v126
	v_exp_f32_e32 v177, v127
	v_exp_f32_e32 v179, v128
	v_exp_f32_e32 v254, v129
	v_add_f32_e32 v219, v0, v219
	v_add_f32_e32 v219, v177, v219
	v_cvt_pk_fp8_f32 v249, v0, v177
	v_add_f32_e32 v219, v179, v219
	v_add_f32_e32 v219, v254, v219
	v_cvt_pk_fp8_f32 v249, v179, v254 op_sel:[0,0,1]
	ds_read_b128 v[122:125], v185 offset:32768
	ds_read_b128 v[126:129], v186 offset:32768
	s_waitcnt lgkmcnt(4)
	v_mfma_scale_f32_32x32x64_f8f6f4 v[82:97], v[114:121], v[138:145], v[82:97], v194, v193 op_sel_hi:[0,0,0]
	v_exp_f32_e32 v0, v98
	v_exp_f32_e32 v177, v99
	v_exp_f32_e32 v179, v100
	v_exp_f32_e32 v254, v101
	v_add_f32_e32 v219, v0, v219
	v_add_f32_e32 v219, v177, v219
	v_cvt_pk_fp8_f32 v250, v0, v177
	v_add_f32_e32 v219, v179, v219
	v_add_f32_e32 v219, v254, v219
	v_cvt_pk_fp8_f32 v250, v179, v254 op_sel:[0,0,1]
	s_waitcnt lgkmcnt(2)
	v_mfma_scale_f32_32x32x64_f8f6f4 v[66:81], v[222:229], v[138:145], v[66:81], v194, v193 op_sel_hi:[0,0,0]
	ds_read_b128 v[222:225], v185 offset:34816
	ds_read_b128 v[226:229], v186 offset:34816
	v_exp_f32_e32 v0, v102
	v_exp_f32_e32 v177, v103
	v_exp_f32_e32 v179, v104
	v_exp_f32_e32 v254, v105
	v_add_f32_e32 v219, v0, v219
	v_add_f32_e32 v219, v177, v219
	v_cvt_pk_fp8_f32 v251, v0, v177
	v_add_f32_e32 v219, v179, v219
	v_add_f32_e32 v219, v254, v219
	v_cvt_pk_fp8_f32 v251, v179, v254 op_sel:[0,0,1]
	v_exp_f32_e32 v0, v106
	v_exp_f32_e32 v177, v107
	v_exp_f32_e32 v179, v108
	v_exp_f32_e32 v254, v109
	v_add_f32_e32 v219, v0, v219
	v_add_f32_e32 v219, v177, v219
	v_cvt_pk_fp8_f32 v252, v0, v177
	v_add_f32_e32 v219, v179, v219
	v_add_f32_e32 v219, v254, v219
	v_cvt_pk_fp8_f32 v252, v179, v254 op_sel:[0,0,1]
	s_waitcnt lgkmcnt(2)
	v_mfma_scale_f32_32x32x64_f8f6f4 v[82:97], v[122:129], v[130:137], v[82:97], v194, v193 op_sel_hi:[0,0,0]
	v_exp_f32_e32 v0, v110
	v_exp_f32_e32 v177, v111
	v_exp_f32_e32 v179, v112
	v_exp_f32_e32 v254, v113
	v_add_f32_e32 v219, v0, v219
	v_add_f32_e32 v219, v177, v219
	v_cvt_pk_fp8_f32 v253, v0, v177
	v_add_f32_e32 v219, v179, v219
	v_add_f32_e32 v219, v254, v219
	v_cvt_pk_fp8_f32 v253, v179, v254 op_sel:[0,0,1]
	ds_read_b128 v[122:125], v185 offset:43008
	ds_read_b128 v[126:129], v186 offset:43008
	ds_read_b128 v[114:117], v185 offset:45056
	ds_read_b128 v[118:121], v186 offset:45056
	ds_read_b128 v[106:109], v185 offset:47104
	ds_read_b128 v[110:113], v186 offset:47104
	ds_read_b128 v[98:101], v185 offset:49152
	ds_read_b128 v[102:105], v186 offset:49152
	s_waitcnt lgkmcnt(8)
	v_mfma_scale_f32_32x32x64_f8f6f4 v[66:81], v[222:229], v[130:137], v[66:81], v194, v193 op_sel_hi:[0,0,0]
	v_mov_b32_e32 v0, v219
	s_nop 1
	v_permlane32_swap_b32_e32 v219, v0
	v_add_f32_e32 v219, v219, v0
	v_fma_f32 v209, v209, v221, v219
	v_max_f32_e32 v177, v82, v83
	v_max3_f32 v177, v177, v84, v85
	v_max3_f32 v177, v177, v86, v87
	v_max3_f32 v177, v177, v88, v89
	v_max3_f32 v177, v177, v90, v91
	v_max3_f32 v177, v177, v92, v93
	v_max3_f32 v177, v177, v94, v95
	v_max3_f32 v177, v177, v96, v97
	s_waitcnt lgkmcnt(6)
	v_mfma_scale_f32_32x32x64_f8f6f4 v[50:65], v[246:253], v[122:129], v[50:65], v194, v194 op_sel_hi:[0,0,0]
	s_waitcnt lgkmcnt(4)
	v_mfma_scale_f32_32x32x64_f8f6f4 v[34:49], v[246:253], v[114:121], v[34:49], v194, v194 op_sel_hi:[0,0,0]
	s_waitcnt vmcnt(0)
	s_waitcnt lgkmcnt(0)
	s_barrier
	v_max_f32_e32 v0, v66, v67
	v_max3_f32 v0, v0, v68, v69
	v_max3_f32 v0, v0, v70, v71
	v_max3_f32 v0, v0, v72, v73
	s_waitcnt lgkmcnt(2)
	v_mfma_scale_f32_32x32x64_f8f6f4 v[18:33], v[246:253], v[106:113], v[18:33], v194, v194 op_sel_hi:[0,0,0]
	s_add_i32 m0, s98, 0xa800
	s_nop 0
	global_load_lds_dwordx4 v176, s[18:19]
	s_add_i32 m0, s98, 0xc800
	s_nop 0
	global_load_lds_dwordx4 v178, s[16:17]
	v_add_u32_e32 v176, 0x2000, v176
	v_add_u32_e32 v178, 0x20000, v178
	v_max3_f32 v0, v0, v74, v75
	v_max3_f32 v0, v0, v76, v77
	v_max3_f32 v0, v0, v78, v79
	v_max3_f32 v0, v0, v80, v81
	s_waitcnt lgkmcnt(0)
	v_mfma_scale_f32_32x32x64_f8f6f4 v[2:17], v[246:253], v[98:105], v[2:17], v194, v194 op_sel_hi:[0,0,0]
	v_max_f32_e32 v177, v177, v0
	v_mov_b32_e32 v0, v177
	v_mov_b32_e32 v218, 1.0
	s_nop 0
	v_permlane32_swap_b32_e32 v177, v0
	v_max_f32_e32 v177, v177, v0
	v_cmp_ge_f32_e32 vcc, s90, v177
	s_cmp_eq_u64 vcc, exec
	s_cbranch_scc0 .Lmla_s5_newmax
; __device__ __forceinline__ void finishSM9(f32x16& p0, f32x16& p1, float alpha, float& l_reg, v8i32& p8) {
; #pragma unroll
;   for (int r = 0; r < 16; ++r) { p0[r] = __builtin_amdgcn_exp2f(p0[r]); p1[r] = __builtin_amdgcn_exp2f(p1[r]); }
;   float ps = 0;
; #pragma unroll
;   for (int r = 0; r < 16; ++r) ps += p0[r];
; #pragma unroll
;   for (int r = 0; r < 16; ++r) ps += p1[r];
;   { auto rr = __builtin_amdgcn_permlane32_swap(__float_as_uint(ps), __float_as_uint(ps), false, false);
;     ps = __uint_as_float(rr[0]) + __uint_as_float(rr[1]); }
;   l_reg = l_reg * alpha + ps;
; #pragma unroll
;   for (int g = 0; g < 4; ++g) {
;     int w = __builtin_amdgcn_cvt_pk_fp8_f32(p0[4 * g], p0[4 * g + 1], 0, false); p8[g] = __builtin_amdgcn_cvt_pk_fp8_f32(p0[4 * g + 2], p0[4 * g + 3], w, true);
;     int u = __builtin_amdgcn_cvt_pk_fp8_f32(p1[4 * g], p1[4 * g + 1], 0, false); p8[4 + g] = __builtin_amdgcn_cvt_pk_fp8_f32(p1[4 * g + 2], p1[4 * g + 3], u, true); }
; }
; __device__ __forceinline__ void pv8(f32x16* o, const char* Vt, const v8i32 p8, int r32, int hi) {
;   const int sw = (r32 >> 2) & 3, a0 = r32 * 64 + (((hi * 2) ^ sw) << 4), a1 = r32 * 64 + (((hi * 2 + 1) ^ sw) << 4);
; #pragma unroll
;   for (int d0 = 0; d0 < 4; ++d0) {
;     const v8i32 vf = cat8(*reinterpret_cast<const v4i32*>(Vt + d0 * 2048 + a0), *reinterpret_cast<const v4i32*>(Vt + d0 * 2048 + a1));
;     o[d0] = __builtin_amdgcn_mfma_scale_f32_32x32x64_f8f6f4(p8, vf, o[d0], 0, 0, 0, 127, 0, 127); }
; }
; __device__ __forceinline__ void qkt9(f32x16& p0, f32x16& p1, const char* Kn, const char* Kr, const v8i32* qf, const float init, int r32, int hi) {
; #pragma unroll
;   for (int r = 0; r < 16; ++r) { p0[r] = init; p1[r] = init; }
; #pragma unroll
;   for (int s = 0; s < 2; ++s) { const int c0 = s * 4 + hi * 2;
;     const v8i32 a0 = cat8(*reinterpret_cast<const v4i32*>(Kn + KN8SW(r32, c0)), *reinterpret_cast<const v4i32*>(Kn + KN8SW(r32, c0 + 1)));
;     const v8i32 a1 = cat8(*reinterpret_cast<const v4i32*>(Kn + 4096 + KN8SW(r32, c0)), *reinterpret_cast<const v4i32*>(Kn + 4096 + KN8SW(r32, c0 + 1)));
;     p0 = __builtin_amdgcn_mfma_scale_f32_32x32x64_f8f6f4(a0, qf[s], p0, 0, 0, 0, 127, 0, 124);
;     p1 = __builtin_amdgcn_mfma_scale_f32_32x32x64_f8f6f4(a1, qf[s], p1, 0, 0, 0, 127, 0, 124); }
;   { const int c0 = hi * 2;
.Lmla_s5_cont:
	s_add_i32 s30, s30, 1
	s_cmpk_lt_u32 s30, 42
	s_cbranch_scc1 .Lmla_stag_loop
	ds_read_b128 v[114:117], v215 offset:24576
	ds_read_b128 v[118:121], v216 offset:24576
	ds_read_b128 v[222:225], v215 offset:28672
	ds_read_b128 v[226:229], v216 offset:28672
	v_exp_f32_e32 v0, v82
	v_exp_f32_e32 v177, v83
	v_exp_f32_e32 v179, v84
	v_exp_f32_e32 v254, v85
	v_add_f32_e32 v219, v0, v177
	v_cvt_pk_fp8_f32 v246, v0, v177
	v_add_f32_e32 v219, v179, v219
	v_add_f32_e32 v219, v254, v219
	v_cvt_pk_fp8_f32 v246, v179, v254 op_sel:[0,0,1]
	s_waitcnt lgkmcnt(2)
	v_mfma_scale_f32_32x32x64_f8f6f4 v[114:129], v[114:121], v[146:153], v[230:245], v194, v193 op_sel_hi:[0,0,0]
	v_exp_f32_e32 v0, v86
	v_exp_f32_e32 v177, v87
	v_exp_f32_e32 v179, v88
	v_exp_f32_e32 v254, v89
	v_add_f32_e32 v219, v0, v219
	v_add_f32_e32 v219, v177, v219
	v_cvt_pk_fp8_f32 v247, v0, v177
	v_add_f32_e32 v219, v179, v219
	v_add_f32_e32 v219, v254, v219
	v_cvt_pk_fp8_f32 v247, v179, v254 op_sel:[0,0,1]
	ds_read_b128 v[82:85], v213 offset:24576
	ds_read_b128 v[86:89], v214 offset:24576
	s_waitcnt lgkmcnt(2)
	v_mfma_scale_f32_32x32x64_f8f6f4 v[98:113], v[222:229], v[146:153], v[230:245], v194, v193 op_sel_hi:[0,0,0]
	ds_read_b128 v[222:225], v213 offset:28672
	ds_read_b128 v[226:229], v214 offset:28672
	v_exp_f32_e32 v0, v90
	v_exp_f32_e32 v177, v91
	v_exp_f32_e32 v179, v92
	v_exp_f32_e32 v254, v93
	v_add_f32_e32 v219, v0, v219
	v_add_f32_e32 v219, v177, v219
	v_cvt_pk_fp8_f32 v248, v0, v177
	v_add_f32_e32 v219, v179, v219
	v_add_f32_e32 v219, v254, v219
	v_cvt_pk_fp8_f32 v248, v179, v254 op_sel:[0,0,1]
	v_exp_f32_e32 v0, v94
	v_exp_f32_e32 v177, v95
	v_exp_f32_e32 v179, v96
	v_exp_f32_e32 v254, v97
	v_add_f32_e32 v219, v0, v219
	v_add_f32_e32 v219, v177, v219
	v_cvt_pk_fp8_f32 v249, v0, v177
	v_add_f32_e32 v219, v179, v219
	v_add_f32_e32 v219, v254, v219
	v_cvt_pk_fp8_f32 v249, v179, v254 op_sel:[0,0,1]
	ds_read_b128 v[90:93], v185 offset:36864
	ds_read_b128 v[94:97], v186 offset:36864
	s_waitcnt lgkmcnt(4)
	v_mfma_scale_f32_32x32x64_f8f6f4 v[114:129], v[82:89], v[138:145], v[114:129], v194, v193 op_sel_hi:[0,0,0]
	v_exp_f32_e32 v0, v66
	v_exp_f32_e32 v177, v67
	v_exp_f32_e32 v179, v68
	v_exp_f32_e32 v254, v69
	v_add_f32_e32 v219, v0, v219
	v_add_f32_e32 v219, v177, v219
	v_cvt_pk_fp8_f32 v250, v0, v177
	v_add_f32_e32 v219, v179, v219
	v_add_f32_e32 v219, v254, v219
	v_cvt_pk_fp8_f32 v250, v179, v254 op_sel:[0,0,1]
	s_waitcnt lgkmcnt(2)
	v_mfma_scale_f32_32x32x64_f8f6f4 v[98:113], v[222:229], v[138:145], v[98:113], v194, v193 op_sel_hi:[0,0,0]
	ds_read_b128 v[222:225], v185 offset:38912
	ds_read_b128 v[226:229], v186 offset:38912
	v_exp_f32_e32 v0, v70
	v_exp_f32_e32 v177, v71
	v_exp_f32_e32 v179, v72
	v_exp_f32_e32 v254, v73
	v_add_f32_e32 v219, v0, v219
	v_add_f32_e32 v219, v177, v219
	v_cvt_pk_fp8_f32 v251, v0, v177
	v_add_f32_e32 v219, v179, v219
	v_add_f32_e32 v219, v254, v219
	v_cvt_pk_fp8_f32 v251, v179, v254 op_sel:[0,0,1]
	v_exp_f32_e32 v0, v74
	v_exp_f32_e32 v177, v75
	v_exp_f32_e32 v179, v76
	v_exp_f32_e32 v254, v77
	v_add_f32_e32 v219, v0, v219
	v_add_f32_e32 v219, v177, v219
	v_cvt_pk_fp8_f32 v252, v0, v177
	v_add_f32_e32 v219, v179, v219
	v_add_f32_e32 v219, v254, v219
	v_cvt_pk_fp8_f32 v252, v179, v254 op_sel:[0,0,1]
	s_waitcnt lgkmcnt(2)
	v_mfma_scale_f32_32x32x64_f8f6f4 v[114:129], v[90:97], v[130:137], v[114:129], v194, v193 op_sel_hi:[0,0,0]
	v_exp_f32_e32 v0, v78
	v_exp_f32_e32 v177, v79
	v_exp_f32_e32 v179, v80
	v_exp_f32_e32 v254, v81
	v_add_f32_e32 v219, v0, v219
	v_add_f32_e32 v219, v177, v219
	v_cvt_pk_fp8_f32 v253, v0, v177
	v_add_f32_e32 v219, v179, v219
	v_add_f32_e32 v219, v254, v219
	v_cvt_pk_fp8_f32 v253, v179, v254 op_sel:[0,0,1]
	ds_read_b128 v[90:93], v185 offset:0
	ds_read_b128 v[94:97], v186 offset:0
	ds_read_b128 v[82:85], v185 offset:2048
	ds_read_b128 v[86:89], v186 offset:2048
	ds_read_b128 v[74:77], v185 offset:4096
	ds_read_b128 v[78:81], v186 offset:4096
	ds_read_b128 v[66:69], v185 offset:6144
	ds_read_b128 v[70:73], v186 offset:6144
	s_waitcnt lgkmcnt(8)
	v_mfma_scale_f32_32x32x64_f8f6f4 v[98:113], v[222:229], v[130:137], v[98:113], v194, v193 op_sel_hi:[0,0,0]
	v_mov_b32_e32 v0, v219
	s_nop 1
	v_permlane32_swap_b32_e32 v219, v0
	v_add_f32_e32 v219, v219, v0
	v_fma_f32 v209, v209, v218, v219
	v_max_f32_e32 v177, v114, v115
	v_max3_f32 v177, v177, v116, v117
	v_max3_f32 v177, v177, v118, v119
	v_max3_f32 v177, v177, v120, v121
	v_max3_f32 v177, v177, v122, v123
	v_max3_f32 v177, v177, v124, v125
	v_max3_f32 v177, v177, v126, v127
	v_max3_f32 v177, v177, v128, v129
	s_waitcnt lgkmcnt(6)
	v_mfma_scale_f32_32x32x64_f8f6f4 v[50:65], v[246:253], v[90:97], v[50:65], v194, v194 op_sel_hi:[0,0,0]
	s_waitcnt lgkmcnt(4)
	v_mfma_scale_f32_32x32x64_f8f6f4 v[34:49], v[246:253], v[82:89], v[34:49], v194, v194 op_sel_hi:[0,0,0]
	s_waitcnt vmcnt(0)
	s_waitcnt lgkmcnt(0)
	s_barrier
	v_max_f32_e32 v0, v98, v99
	v_max3_f32 v0, v0, v100, v101
	v_max3_f32 v0, v0, v102, v103
	v_max3_f32 v0, v0, v104, v105
	s_waitcnt lgkmcnt(2)
	v_mfma_scale_f32_32x32x64_f8f6f4 v[18:33], v[246:253], v[74:81], v[18:33], v194, v194 op_sel_hi:[0,0,0]
	s_add_i32 m0, s98, 0x0
	s_nop 0
	global_load_lds_dwordx4 v176, s[18:19]
	s_add_i32 m0, s98, 0x4000
	s_nop 0
	global_load_lds_dwordx4 v178, s[16:17]
	v_add_u32_e32 v176, 0x2000, v176
	v_add_u32_e32 v178, 0x20000, v178
	v_max3_f32 v0, v0, v106, v107
	v_max3_f32 v0, v0, v108, v109
	v_max3_f32 v0, v0, v110, v111
	v_max3_f32 v0, v0, v112, v113
	s_waitcnt lgkmcnt(0)
	v_mfma_scale_f32_32x32x64_f8f6f4 v[2:17], v[246:253], v[66:73], v[2:17], v194, v194 op_sel_hi:[0,0,0]
	v_max_f32_e32 v177, v177, v0
	v_mov_b32_e32 v0, v177
	v_mov_b32_e32 v221, 1.0
	s_nop 0
	v_permlane32_swap_b32_e32 v177, v0
	v_max_f32_e32 v177, v177, v0
	v_cmp_ge_f32_e32 vcc, s90, v177
	s_cmp_eq_u64 vcc, exec
	s_cbranch_scc0 .Lmla_q0_newmax
; __device__ __forceinline__ void finishSM9(f32x16& p0, f32x16& p1, float alpha, float& l_reg, v8i32& p8) {
; #pragma unroll
;   for (int r = 0; r < 16; ++r) { p0[r] = __builtin_amdgcn_exp2f(p0[r]); p1[r] = __builtin_amdgcn_exp2f(p1[r]); }
;   float ps = 0;
; #pragma unroll
;   for (int r = 0; r < 16; ++r) ps += p0[r];
; #pragma unroll
;   for (int r = 0; r < 16; ++r) ps += p1[r];
;   { auto rr = __builtin_amdgcn_permlane32_swap(__float_as_uint(ps), __float_as_uint(ps), false, false);
;     ps = __uint_as_float(rr[0]) + __uint_as_float(rr[1]); }
;   l_reg = l_reg * alpha + ps;
; #pragma unroll
;   for (int g = 0; g < 4; ++g) {
;     int w = __builtin_amdgcn_cvt_pk_fp8_f32(p0[4 * g], p0[4 * g + 1], 0, false); p8[g] = __builtin_amdgcn_cvt_pk_fp8_f32(p0[4 * g + 2], p0[4 * g + 3], w, true);
;     int u = __builtin_amdgcn_cvt_pk_fp8_f32(p1[4 * g], p1[4 * g + 1], 0, false); p8[4 + g] = __builtin_amdgcn_cvt_pk_fp8_f32(p1[4 * g + 2], p1[4 * g + 3], u, true); }
; }
; __device__ __forceinline__ void pv8(f32x16* o, const char* Vt, const v8i32 p8, int r32, int hi) {
;   const int sw = (r32 >> 2) & 3, a0 = r32 * 64 + (((hi * 2) ^ sw) << 4), a1 = r32 * 64 + (((hi * 2 + 1) ^ sw) << 4);
; #pragma unroll
;   for (int d0 = 0; d0 < 4; ++d0) {
;     const v8i32 vf = cat8(*reinterpret_cast<const v4i32*>(Vt + d0 * 2048 + a0), *reinterpret_cast<const v4i32*>(Vt + d0 * 2048 + a1));
;     o[d0] = __builtin_amdgcn_mfma_scale_f32_32x32x64_f8f6f4(p8, vf, o[d0], 0, 0, 0, 127, 0, 127); }
; }
; __device__ __forceinline__ void qkt9(f32x16& p0, f32x16& p1, const char* Kn, const char* Kr, const v8i32* qf, const float init, int r32, int hi) {
; #pragma unroll
;   for (int r = 0; r < 16; ++r) { p0[r] = init; p1[r] = init; }
; #pragma unroll
;   for (int s = 0; s < 2; ++s) { const int c0 = s * 4 + hi * 2;
;     const v8i32 a0 = cat8(*reinterpret_cast<const v4i32*>(Kn + KN8SW(r32, c0)), *reinterpret_cast<const v4i32*>(Kn + KN8SW(r32, c0 + 1)));
;     const v8i32 a1 = cat8(*reinterpret_cast<const v4i32*>(Kn + 4096 + KN8SW(r32, c0)), *reinterpret_cast<const v4i32*>(Kn + 4096 + KN8SW(r32, c0 + 1)));
;     p0 = __builtin_amdgcn_mfma_scale_f32_32x32x64_f8f6f4(a0, qf[s], p0, 0, 0, 0, 127, 0, 124);
;     p1 = __builtin_amdgcn_mfma_scale_f32_32x32x64_f8f6f4(a1, qf[s], p1, 0, 0, 0, 127, 0, 124); }
;   { const int c0 = hi * 2;
.Lmla_q0_cont:
	ds_read_b128 v[82:85], v215 offset:51200
	ds_read_b128 v[86:89], v216 offset:51200
	ds_read_b128 v[222:225], v215 offset:55296
	ds_read_b128 v[226:229], v216 offset:55296
	v_exp_f32_e32 v0, v114
	v_exp_f32_e32 v177, v115
	v_exp_f32_e32 v179, v116
	v_exp_f32_e32 v254, v117
	v_add_f32_e32 v219, v0, v177
	v_cvt_pk_fp8_f32 v246, v0, v177
	v_add_f32_e32 v219, v179, v219
	v_add_f32_e32 v219, v254, v219
	v_cvt_pk_fp8_f32 v246, v179, v254 op_sel:[0,0,1]
	s_waitcnt lgkmcnt(2)
	v_mfma_scale_f32_32x32x64_f8f6f4 v[82:97], v[82:89], v[146:153], v[230:245], v194, v193 op_sel_hi:[0,0,0]
	v_exp_f32_e32 v0, v118
	v_exp_f32_e32 v177, v119
	v_exp_f32_e32 v179, v120
	v_exp_f32_e32 v254, v121
	v_add_f32_e32 v219, v0, v219
	v_add_f32_e32 v219, v177, v219
	v_cvt_pk_fp8_f32 v247, v0, v177
	v_add_f32_e32 v219, v179, v219
	v_add_f32_e32 v219, v254, v219
	v_cvt_pk_fp8_f32 v247, v179, v254 op_sel:[0,0,1]
	ds_read_b128 v[114:117], v213 offset:51200
	ds_read_b128 v[118:121], v214 offset:51200
	s_waitcnt lgkmcnt(2)
	v_mfma_scale_f32_32x32x64_f8f6f4 v[66:81], v[222:229], v[146:153], v[230:245], v194, v193 op_sel_hi:[0,0,0]
	ds_read_b128 v[222:225], v213 offset:55296
	ds_read_b128 v[226:229], v214 offset:55296
	v_exp_f32_e32 v0, v122
	v_exp_f32_e32 v177, v123
	v_exp_f32_e32 v179, v124
	v_exp_f32_e32 v254, v125
	v_add_f32_e32 v219, v0, v219
	v_add_f32_e32 v219, v177, v219
	v_cvt_pk_fp8_f32 v248, v0, v177
	v_add_f32_e32 v219, v179, v219
	v_add_f32_e32 v219, v254, v219
	v_cvt_pk_fp8_f32 v248, v179, v254 op_sel:[0,0,1]
	v_exp_f32_e32 v0, v126
	v_exp_f32_e32 v177, v127
	v_exp_f32_e32 v179, v128
	v_exp_f32_e32 v254, v129
	v_add_f32_e32 v219, v0, v219
	v_add_f32_e32 v219, v177, v219
	v_cvt_pk_fp8_f32 v249, v0, v177
	v_add_f32_e32 v219, v179, v219
	v_add_f32_e32 v219, v254, v219
	v_cvt_pk_fp8_f32 v249, v179, v254 op_sel:[0,0,1]
	ds_read_b128 v[122:125], v185 offset:59392
	ds_read_b128 v[126:129], v186 offset:59392
	s_waitcnt lgkmcnt(4)
	v_mfma_scale_f32_32x32x64_f8f6f4 v[82:97], v[114:121], v[138:145], v[82:97], v194, v193 op_sel_hi:[0,0,0]
	v_exp_f32_e32 v0, v98
	v_exp_f32_e32 v177, v99
	v_exp_f32_e32 v179, v100
	v_exp_f32_e32 v254, v101
	v_add_f32_e32 v219, v0, v219
	v_add_f32_e32 v219, v177, v219
	v_cvt_pk_fp8_f32 v250, v0, v177
	v_add_f32_e32 v219, v179, v219
	v_add_f32_e32 v219, v254, v219
	v_cvt_pk_fp8_f32 v250, v179, v254 op_sel:[0,0,1]
	s_waitcnt lgkmcnt(2)
	v_mfma_scale_f32_32x32x64_f8f6f4 v[66:81], v[222:229], v[138:145], v[66:81], v194, v193 op_sel_hi:[0,0,0]
	ds_read_b128 v[222:225], v185 offset:61440
	ds_read_b128 v[226:229], v186 offset:61440
	v_exp_f32_e32 v0, v102
	v_exp_f32_e32 v177, v103
	v_exp_f32_e32 v179, v104
	v_exp_f32_e32 v254, v105
	v_add_f32_e32 v219, v0, v219
	v_add_f32_e32 v219, v177, v219
	v_cvt_pk_fp8_f32 v251, v0, v177
	v_add_f32_e32 v219, v179, v219
	v_add_f32_e32 v219, v254, v219
	v_cvt_pk_fp8_f32 v251, v179, v254 op_sel:[0,0,1]
	v_exp_f32_e32 v0, v106
	v_exp_f32_e32 v177, v107
	v_exp_f32_e32 v179, v108
	v_exp_f32_e32 v254, v109
	v_add_f32_e32 v219, v0, v219
	v_add_f32_e32 v219, v177, v219
	v_cvt_pk_fp8_f32 v252, v0, v177
	v_add_f32_e32 v219, v179, v219
	v_add_f32_e32 v219, v254, v219
	v_cvt_pk_fp8_f32 v252, v179, v254 op_sel:[0,0,1]
	s_waitcnt lgkmcnt(2)
	v_mfma_scale_f32_32x32x64_f8f6f4 v[82:97], v[122:129], v[130:137], v[82:97], v194, v193 op_sel_hi:[0,0,0]
	v_exp_f32_e32 v0, v110
	v_exp_f32_e32 v177, v111
	v_exp_f32_e32 v179, v112
	v_exp_f32_e32 v254, v113
	v_add_f32_e32 v219, v0, v219
	v_add_f32_e32 v219, v177, v219
	v_cvt_pk_fp8_f32 v253, v0, v177
	v_add_f32_e32 v219, v179, v219
	v_add_f32_e32 v219, v254, v219
	v_cvt_pk_fp8_f32 v253, v179, v254 op_sel:[0,0,1]
	ds_read_b128 v[122:125], v185 offset:8192
	ds_read_b128 v[126:129], v186 offset:8192
	ds_read_b128 v[114:117], v185 offset:10240
	ds_read_b128 v[118:121], v186 offset:10240
	ds_read_b128 v[106:109], v185 offset:12288
	ds_read_b128 v[110:113], v186 offset:12288
	ds_read_b128 v[98:101], v185 offset:14336
	ds_read_b128 v[102:105], v186 offset:14336
	s_waitcnt lgkmcnt(8)
	v_mfma_scale_f32_32x32x64_f8f6f4 v[66:81], v[222:229], v[130:137], v[66:81], v194, v193 op_sel_hi:[0,0,0]
	v_mov_b32_e32 v0, v219
	s_nop 1
	v_permlane32_swap_b32_e32 v219, v0
	v_add_f32_e32 v219, v219, v0
	v_fma_f32 v209, v209, v221, v219
	v_max_f32_e32 v177, v82, v83
	v_max3_f32 v177, v177, v84, v85
	v_max3_f32 v177, v177, v86, v87
	v_max3_f32 v177, v177, v88, v89
	v_max3_f32 v177, v177, v90, v91
	v_max3_f32 v177, v177, v92, v93
	v_max3_f32 v177, v177, v94, v95
	v_max3_f32 v177, v177, v96, v97
	s_waitcnt lgkmcnt(6)
	v_mfma_scale_f32_32x32x64_f8f6f4 v[50:65], v[246:253], v[122:129], v[50:65], v194, v194 op_sel_hi:[0,0,0]
	s_waitcnt lgkmcnt(4)
	v_mfma_scale_f32_32x32x64_f8f6f4 v[34:49], v[246:253], v[114:121], v[34:49], v194, v194 op_sel_hi:[0,0,0]
	s_waitcnt vmcnt(0)
	s_waitcnt lgkmcnt(0)
	s_barrier
	v_max_f32_e32 v0, v66, v67
	v_max3_f32 v0, v0, v68, v69
	v_max3_f32 v0, v0, v70, v71
	v_max3_f32 v0, v0, v72, v73
	s_waitcnt lgkmcnt(2)
	v_mfma_scale_f32_32x32x64_f8f6f4 v[18:33], v[246:253], v[106:113], v[18:33], v194, v194 op_sel_hi:[0,0,0]
	v_max3_f32 v0, v0, v74, v75
	v_max3_f32 v0, v0, v76, v77
	v_max3_f32 v0, v0, v78, v79
	v_max3_f32 v0, v0, v80, v81
	s_waitcnt lgkmcnt(0)
	v_mfma_scale_f32_32x32x64_f8f6f4 v[2:17], v[246:253], v[98:105], v[2:17], v194, v194 op_sel_hi:[0,0,0]
	v_max_f32_e32 v177, v177, v0
	v_mov_b32_e32 v0, v177
	v_mov_b32_e32 v218, 1.0
	s_nop 0
	v_permlane32_swap_b32_e32 v177, v0
	v_max_f32_e32 v177, v177, v0
	v_cmp_ge_f32_e32 vcc, s90, v177
	s_cmp_eq_u64 vcc, exec
	s_cbranch_scc0 .Lmla_q1_newmax
